# MLA: waves 4-7 staggered by the P.V segment (their pair barrier moved before P.V of the 2nd tile), V ring deepened to 8 slots
# baseline (speedup 1.0000x reference)
.LBB0_1174:
	v_readfirstlane_b32 s64, v206
	s_nop 3
	s_lshr_b32 s64, s64, 8
	s_mov_b32 s66, 0
	s_mov_b32 s67, 0x8000
	s_or_b64 exec, exec, s[0:1]
	s_waitcnt lgkmcnt(1)
	v_max_f32_e32 v0, v11, v11
	v_max_f32_e32 v1, v9, v9
	v_max_f32_e32 v0, v1, v0
	s_waitcnt lgkmcnt(0)
	v_max_f32_e32 v1, v10, v10
	v_max_f32_e32 v8, v8, v8
	v_max_f32_e32 v1, v8, v1
	v_mul_f32_e32 v0, 0x42c00000, v0
	v_and_b32_e32 v8, 0x7fffffff, v6
	v_mul_f32_e32 v0, v1, v0
	ds_bpermute_b32 v8, v7, v8
	v_mul_f32_e32 v1, 0x3e16c740, v0
	v_and_b32_e32 v0, 0x7fffffff, v4
	ds_bpermute_b32 v0, v7, v0
	v_max_f32_e64 v6, |v6|, |v6|
	s_waitcnt lgkmcnt(1)
	v_max_f32_e32 v8, v8, v8
	ds_bpermute_b32 v7, v7, v14
	v_max_f32_e32 v6, v6, v8
	s_waitcnt lgkmcnt(1)
	v_max_f32_e32 v0, v0, v0
	v_max_f32_e64 v4, |v4|, |v4|
	v_max_f32_e32 v0, v4, v0
	ds_bpermute_b32 v4, v5, v6
	ds_bpermute_b32 v9, v5, v0
	s_waitcnt lgkmcnt(2)
	v_max_f32_e32 v7, v7, v7
	v_max_f32_e32 v8, v14, v14
	v_max_f32_e32 v7, v8, v7
	s_waitcnt lgkmcnt(1)
	v_max_f32_e32 v4, v4, v4
	ds_bpermute_b32 v5, v5, v7
	v_max_f32_e32 v4, v6, v4
	s_waitcnt lgkmcnt(1)
	v_max_f32_e32 v6, v9, v9
	ds_bpermute_b32 v8, v3, v4
	v_max_f32_e32 v0, v0, v6
	ds_bpermute_b32 v6, v3, v0
	s_waitcnt lgkmcnt(2)
	v_max_f32_e32 v5, v5, v5
	v_max_f32_e32 v5, v7, v5
	s_waitcnt lgkmcnt(1)
	v_max_f32_e32 v7, v8, v8
	ds_bpermute_b32 v3, v3, v5
	v_max_f32_e32 v4, v4, v7
	s_waitcnt lgkmcnt(1)
	v_max_f32_e32 v6, v6, v6
	ds_bpermute_b32 v7, v2, v4
	v_max_f32_e32 v0, v0, v6
	ds_bpermute_b32 v6, v2, v0
	s_waitcnt lgkmcnt(2)
	v_max_f32_e32 v3, v3, v3
	v_max_f32_e32 v3, v5, v3
	s_waitcnt lgkmcnt(1)
	v_max_f32_e32 v5, v7, v7
	ds_bpermute_b32 v2, v2, v3
	v_max_f32_e32 v4, v4, v5
	s_waitcnt lgkmcnt(1)
	v_max_f32_e32 v5, v6, v6
	ds_bpermute_b32 v6, v217, v4
	v_max_f32_e32 v0, v0, v5
	s_waitcnt lgkmcnt(1)
	v_max_f32_e32 v2, v2, v2
	ds_bpermute_b32 v5, v217, v0
	v_max_f32_e32 v2, v3, v2
	s_waitcnt lgkmcnt(1)
	v_max_f32_e32 v3, v6, v6
	ds_bpermute_b32 v6, v217, v2
	v_max_f32_e32 v3, v4, v3
	s_waitcnt lgkmcnt(1)
	v_max_f32_e32 v4, v5, v5
	v_max_f32_e32 v0, v0, v4
	ds_bpermute_b32 v4, v218, v3
	s_waitcnt lgkmcnt(1)
	v_max_f32_e32 v5, v6, v6
	ds_bpermute_b32 v6, v218, v0
	v_max_f32_e32 v2, v2, v5
	ds_bpermute_b32 v5, v218, v2
	s_mov_b32 s1, 0x42700000
	s_waitcnt lgkmcnt(2)
	v_max_f32_e32 v4, v4, v4
	v_cmp_gt_f32_e32 vcc, s1, v1
	v_max_f32_e32 v3, v3, v4
	s_waitcnt lgkmcnt(1)
	v_max_f32_e32 v4, v6, v6
	v_cndmask_b32_e64 v1, 0, 1, vcc
	v_max_f32_e32 v4, v0, v4
	s_waitcnt lgkmcnt(0)
	v_max_f32_e32 v0, v5, v5
	v_readfirstlane_b32 s0, v1
	v_mul_f32_e32 v1, 0x42800000, v3
	v_max_f32_e32 v0, v2, v0
	v_mul_f32_e32 v1, v4, v1
	v_pk_mul_f32 v[0:1], v[0:1], s[12:13]
	s_bitcmp1_b32 s0, 0
	v_add_f32_e32 v0, v0, v1
	v_cmp_gt_f32_e32 vcc, s1, v0
	v_readlane_b32 s4, v252, 39
	s_cselect_b64 s[2:3], -1, 0
	v_cndmask_b32_e64 v0, 0, 1, vcc
	v_readlane_b32 s5, v252, 40
	v_readfirstlane_b32 s0, v0
	s_bitcmp1_b32 s0, 0
	s_cselect_b64 s[0:1], -1, 0
	s_and_b64 vcc, exec, s[4:5]
	s_cbranch_vccz .LBB0_1225
	s_xor_b64 s[2:3], s[2:3], -1
	s_add_u32 s4, s94, 0x1b600000
	s_addc_u32 s5, s95, 0
	s_add_u32 s30, s94, 0x3600000
	s_addc_u32 s31, s95, 0
	s_add_u32 s34, s94, 0x12600000
	s_addc_u32 s35, s95, 0
	s_lshl_b32 s36, s51, 5
	v_lshrrev_b32_e32 v1, 5, v158
	s_ashr_i32 s37, s36, 31
	v_lshrrev_b32_e32 v4, 2, v160
	v_bfe_u32 v5, v160, 2, 2
	v_bitop3_b32 v4, v4, v1, 3 bitop3:0x6c
	s_cmp_gt_i32 s51, 3
	v_lshlrev_b32_e32 v148, 4, v158
	v_lshlrev_b32_e32 v8, 4, v4
	v_bitop3_b32 v4, v1, v5, 2 bitop3:0x36
	s_cselect_b64 s[38:39], -1, 0
	s_add_i32 s8, s51, 8
	v_lshl_or_b32 v161, s51, 3, v33
	v_lshlrev_b32_e32 v9, 4, v4
	v_lshl_add_u64 v[4:5], s[94:95], 0, v[148:149]
	s_mov_b64 s[6:7], 0xf600000
	s_cmp_lt_i32 s51, 4
	v_and_b32_e32 v159, 31, v160
	v_lshrrev_b32_e32 v3, 1, v161
	v_lshl_add_u64 v[140:141], v[4:5], 0, s[6:7]
	s_movk_i32 s6, 0xc0
	s_cselect_b64 s[40:41], -1, 0
	v_xor_b32_e32 v2, v3, v160
	v_mad_u32_u24 v12, v159, s6, 0
	s_and_b64 s[6:7], s[40:41], exec
	v_lshlrev_b32_e32 v2, 3, v2
	s_cselect_b32 s6, s8, s51
	v_and_b32_e32 v2, 56, v2
	v_lshrrev_b32_e32 v6, 1, v160
	v_lshlrev_b32_e32 v13, 6, v159
	s_lshl_b32 s44, s6, 10
	s_mov_b64 s[6:7], 0xac400
	v_bitop3_b32 v6, v6, v1, 7 bitop3:0x6c
	v_sub_u32_e32 v13, v12, v13
	s_lshl_b32 s42, s51, 10
	v_lshl_add_u64 v[142:143], v[4:5], 0, s[6:7]
	v_lshlrev_b32_e32 v4, 1, v2
	v_mov_b32_e32 v5, v149
	v_lshl_add_u32 v173, v6, 4, v13
	v_cmp_eq_u32_e32 vcc, 0, v159
	v_mov_b32_e32 v6, 0x3f80
	s_add_i32 s52, s42, 0
	s_add_i32 s53, s44, 0
	v_lshl_add_u64 v[4:5], s[94:95], 0, v[4:5]
	s_mov_b64 s[6:7], 0xc4400
	s_lshl_b32 s46, s8, 10
	v_cndmask_b32_e32 v6, 0, v6, vcc
	s_ashr_i32 s43, s42, 31
	s_ashr_i32 s45, s44, 31
	s_add_i32 s54, s52, 0x6000
	s_add_i32 s55, s53, 0x6000
	v_lshl_add_u64 v[144:145], v[4:5], 0, s[6:7]
	s_mov_b32 s6, 0x5040100
	s_ashr_i32 s47, s46, 31
	s_add_i32 s56, s46, 0
	v_perm_b32 v112, v6, v6, s6
	s_add_u32 s6, s86, s42
	s_addc_u32 s7, s87, s43
	v_bfe_u32 v7, v160, 1, 3
	v_lshl_add_u64 v[146:147], s[6:7], 0, v[148:149]
	s_add_u32 s6, s86, s44
	v_lshlrev_b32_e32 v0, 3, v1
	v_bitop3_b32 v10, v1, v7, 2 bitop3:0x36
	v_bitop3_b32 v11, v1, v7, 4 bitop3:0x36
	v_bitop3_b32 v7, v1, v7, 6 bitop3:0x36
	v_lshlrev_b32_e32 v4, 2, v1
	s_addc_u32 s7, s87, s45
	v_bitop3_b32 v1, v3, 7, v160 bitop3:0x48
	v_lshl_add_u32 v193, v11, 4, v13
	v_lshl_add_u32 v195, v7, 4, v13
	v_lshl_add_u32 v197, v10, 4, v13
	v_lshl_add_u64 v[162:163], s[6:7], 0, v[148:149]
	v_lshlrev_b32_e32 v148, 4, v1
	v_add_u32_e32 v192, 0xc000, v173
	v_add_u32_e32 v194, 0xc000, v193
	v_add_u32_e32 v196, 0xc000, v195
	v_add_u32_e32 v198, 0xc000, v197
	v_mov_b32_e32 v113, v112
	v_mov_b32_e32 v114, v112
	v_mov_b32_e32 v115, v112
	v_lshl_add_u64 v[164:165], s[86:87], 0, v[148:149]
	v_lshlrev_b32_e32 v148, 1, v0
	v_lshlrev_b32_e32 v166, 1, v2
	s_add_i32 s57, s52, 0x9000
	v_lshlrev_b32_e32 v168, 1, v4
	v_add_u32_e32 v199, v12, v8
	v_add_u32_e32 v200, v12, v9
	s_mov_b32 s58, s78
	s_branch .LBB0_1178

.LBB0_1177:
	s_cmp_lg_u32 s64, 0
	s_cbranch_scc1 .Lmla_early_skip3
	s_waitcnt vmcnt(0)
	s_waitcnt vmcnt(0)
	s_barrier
.Lmla_early_skip3:
	v_add_u32_e32 v173, s67, v173
	v_add_u32_e32 v197, s67, v197
	v_add_u32_e32 v193, s67, v193
	v_add_u32_e32 v195, s67, v195
	v_add_u32_e32 v192, s67, v192
	v_add_u32_e32 v198, s67, v198
	v_add_u32_e32 v194, s67, v194
	v_add_u32_e32 v196, s67, v196
	s_sub_i32 s67, 0, s67
	s_xor_b32 s66, s66, 0x8000
	v_exp_f32_e32 v80, v48
	v_exp_f32_e32 v81, v49
	v_exp_f32_e32 v84, v56
	v_exp_f32_e32 v82, v50
	v_exp_f32_e32 v83, v51
	v_exp_f32_e32 v85, v52
	v_exp_f32_e32 v86, v53
	v_exp_f32_e32 v87, v54
	v_exp_f32_e32 v88, v55
	ds_read_b128 v[52:55], v173 offset:53248
	ds_read_b128 v[48:51], v173 offset:49152
	ds_read_b128 v[56:59], v197 offset:49152
	ds_read_b128 v[60:63], v197 offset:53248
	ds_read_b128 v[64:67], v193 offset:49152
	ds_read_b128 v[68:71], v193 offset:53248
	ds_read_b128 v[72:75], v195 offset:49152
	ds_read_b128 v[76:79], v195 offset:53248
	v_add_f32_e32 v32, v32, v80
	v_add_f32_e32 v33, v33, v81
	v_cvt_pk_bf16_f32 v80, v80, v81
	v_add_f32_e32 v34, v34, v82
	v_add_f32_e32 v35, v35, v83
	v_cvt_pk_bf16_f32 v81, v82, v83
	v_add_f32_e32 v32, v32, v85
	v_add_f32_e32 v33, v33, v86
	v_cvt_pk_bf16_f32 v82, v85, v86
	v_add_f32_e32 v34, v34, v87
	v_add_f32_e32 v35, v35, v88
	v_cvt_pk_bf16_f32 v83, v87, v88
	s_waitcnt lgkmcnt(7)
	s_nop 0
	v_mfma_f32_32x32x16_bf16 v[16:31], v[52:55], v[80:83], v[16:31]
	s_waitcnt lgkmcnt(6)
	v_mfma_f32_32x32x16_bf16 v[0:15], v[48:51], v[80:83], v[0:15]
	v_cvt_pk_bf16_f32 v48, v84, v84
	v_mov_b32_e32 v49, v48
	v_mov_b32_e32 v50, v48
	v_mov_b32_e32 v51, v48
	s_waitcnt lgkmcnt(4)
	s_nop 0
	v_mfma_f32_32x32x16_bf16 v[16:31], v[60:63], v[48:51], v[16:31]
	s_waitcnt lgkmcnt(2)
	v_mfma_f32_32x32x16_bf16 v[16:31], v[68:71], v[48:51], v[16:31]
	s_waitcnt lgkmcnt(0)
	v_mfma_f32_32x32x16_bf16 v[16:31], v[76:79], v[48:51], v[16:31]
	v_mfma_f32_32x32x16_bf16 v[0:15], v[56:59], v[48:51], v[0:15]
	v_mfma_f32_32x32x16_bf16 v[0:15], v[64:67], v[48:51], v[0:15]
	v_mfma_f32_32x32x16_bf16 v[0:15], v[72:75], v[48:51], v[0:15]
	s_nop 11
	v_add_f32_e32 v32, v32, v33
	v_add_f32_e32 v34, v34, v35
	v_add_f32_e32 v32, v32, v34
	ds_bpermute_b32 v33, v218, v32
	s_lshl_b32 s48, s59, 1
	v_mov_b32_e32 v169, v149
	s_waitcnt lgkmcnt(0)
	s_barrier
	v_add_f32_e32 v32, v32, v33
	v_div_scale_f32 v33, s[6:7], v32, v32, 1.0
	v_rcp_f32_e32 v34, v33
	v_div_scale_f32 v35, vcc, 1.0, v32, 1.0
	v_fma_f32 v36, -v33, v34, 1.0
	v_fmac_f32_e32 v34, v36, v34
	v_mul_f32_e32 v36, v35, v34
	v_fma_f32 v37, -v33, v36, v35
	v_fmac_f32_e32 v36, v37, v34
	v_fma_f32 v33, -v33, v36, v35
	v_div_fmas_f32 v33, v33, v34, v36
	v_div_fixup_f32 v32, v33, v32, 1.0
	v_lshlrev_b64 v[34:35], 10, v[170:171]
	v_lshl_add_u64 v[34:35], s[34:35], 0, v[34:35]
	v_pk_mul_f32 v[0:1], v[0:1], v[32:33] op_sel_hi:[1,0]
	v_pk_mul_f32 v[2:3], v[2:3], v[32:33] op_sel_hi:[1,0]
	v_lshl_add_u64 v[34:35], v[34:35], 0, s[48:49]
	v_cvt_pk_bf16_f32 v0, v0, v1
	v_cvt_pk_bf16_f32 v1, v2, v3
	v_pk_mul_f32 v[2:3], v[16:17], v[32:33] op_sel_hi:[1,0]
	v_pk_mul_f32 v[16:17], v[18:19], v[32:33] op_sel_hi:[1,0]
	v_lshl_add_u64 v[34:35], v[34:35], 0, v[168:169]
	v_cvt_pk_bf16_f32 v2, v2, v3
	v_cvt_pk_bf16_f32 v3, v16, v17
	global_store_dwordx2 v[34:35], v[0:1], off
	global_store_dwordx2 v[34:35], v[2:3], off offset:64
	v_pk_mul_f32 v[0:1], v[4:5], v[32:33] op_sel_hi:[1,0]
	v_pk_mul_f32 v[2:3], v[6:7], v[32:33] op_sel_hi:[1,0]
	v_cvt_pk_bf16_f32 v0, v0, v1
	v_cvt_pk_bf16_f32 v1, v2, v3
	v_pk_mul_f32 v[2:3], v[20:21], v[32:33] op_sel_hi:[1,0]
	v_pk_mul_f32 v[4:5], v[22:23], v[32:33] op_sel_hi:[1,0]
	v_cvt_pk_bf16_f32 v2, v2, v3
	v_cvt_pk_bf16_f32 v3, v4, v5
	global_store_dwordx2 v[34:35], v[0:1], off offset:16
	global_store_dwordx2 v[34:35], v[2:3], off offset:80
	v_pk_mul_f32 v[0:1], v[8:9], v[32:33] op_sel_hi:[1,0]
	v_pk_mul_f32 v[2:3], v[10:11], v[32:33] op_sel_hi:[1,0]
	v_cvt_pk_bf16_f32 v0, v0, v1
	v_cvt_pk_bf16_f32 v1, v2, v3
	v_pk_mul_f32 v[2:3], v[24:25], v[32:33] op_sel_hi:[1,0]
	v_pk_mul_f32 v[4:5], v[26:27], v[32:33] op_sel_hi:[1,0]
	v_cvt_pk_bf16_f32 v2, v2, v3
	v_cvt_pk_bf16_f32 v3, v4, v5
	global_store_dwordx2 v[34:35], v[0:1], off offset:32
	global_store_dwordx2 v[34:35], v[2:3], off offset:96
	v_pk_mul_f32 v[0:1], v[12:13], v[32:33] op_sel_hi:[1,0]
	v_pk_mul_f32 v[2:3], v[14:15], v[32:33] op_sel_hi:[1,0]
	v_cvt_pk_bf16_f32 v0, v0, v1
	v_cvt_pk_bf16_f32 v1, v2, v3
	v_pk_mul_f32 v[2:3], v[28:29], v[32:33] op_sel_hi:[1,0]
	v_pk_mul_f32 v[4:5], v[30:31], v[32:33] op_sel_hi:[1,0]
	s_add_i32 s58, s58, s82
	v_cvt_pk_bf16_f32 v2, v2, v3
	v_cvt_pk_bf16_f32 v3, v4, v5
	s_cmpk_gt_i32 s58, 0x3ff
	global_store_dwordx2 v[34:35], v[0:1], off offset:48
	global_store_dwordx2 v[34:35], v[2:3], off offset:112
	s_cbranch_scc1 .LBB0_1225

.Lmla_early_skip1:
	v_add_u32_e32 v173, s67, v173
	v_add_u32_e32 v197, s67, v197
	v_add_u32_e32 v193, s67, v193
	v_add_u32_e32 v195, s67, v195
	v_add_u32_e32 v192, s67, v192
	v_add_u32_e32 v198, s67, v198
	v_add_u32_e32 v194, s67, v194
	v_add_u32_e32 v196, s67, v196
	s_sub_i32 s67, 0, s67
	s_xor_b32 s66, s66, 0x8000
	s_mov_b64 s[14:15], 0xc000
	v_lshl_add_u64 v[180:181], v[180:181], 0, s[14:15]
	v_lshl_add_u64 v[182:183], v[182:183], 0, s[14:15]
	s_add_i32 s13, s13, 4
	s_add_i32 s12, s12, 4
	s_mov_b64 s[14:15], 0x200
	s_cmp_gt_u32 s13, 55
	v_lshl_add_u64 v[184:185], v[184:185], 0, s[14:15]
	s_cbranch_scc1 .LBB0_1209

.LBB0_1191:
	s_add_i32 s16, s42, 0
	v_lshl_add_u64 v[188:189], v[184:185], 0, s[10:11]
	s_mov_b64 s[14:15], 0x3600100
	s_add_i32 s18, s16, 0x10000
	v_lshl_add_u64 v[80:81], v[188:189], 0, s[14:15]
	s_add_i32 m0, s18, s66
	s_mov_b64 s[14:15], 0xf60c000
	global_load_lds_dwordx4 v[80:81], off
	v_lshl_add_u64 v[80:81], v[186:187], 0, s[14:15]
	s_mov_b32 m0, s16
	s_and_b64 vcc, exec, s[8:9]
	global_load_lds_dwordx4 v[80:81], off
	s_cbranch_vccnz .LBB0_1193
	v_lshl_add_u64 v[80:81], v[190:191], 0, s[14:15]
	s_mov_b32 m0, s53
	s_nop 0
	global_load_lds_dwordx4 v[80:81], off
.LBB0_1193:
	s_mov_b64 s[14:15], 0x3600180
	s_add_i32 s17, s16, 0x12000
	v_lshl_add_u64 v[80:81], v[188:189], 0, s[14:15]
	s_add_i32 m0, s17, s66
	v_exp_f32_e32 v150, v64
	global_load_lds_dwordx4 v[80:81], off
	ds_read_b128 v[80:83], v199 offset:12288
	ds_read_b128 v[84:87], v199 offset:18432
	ds_read_b128 v[154:157], v200 offset:12288
	ds_read_b128 v[202:205], v200 offset:18432
	ds_read_b128 v[212:215], v199 offset:12352
	ds_read_b128 v[220:223], v199 offset:18496
	ds_read_b128 v[224:227], v200 offset:12352
	ds_read_b128 v[228:231], v200 offset:18496
	ds_read_b128 v[232:235], v199 offset:12416
	ds_read_b128 v[236:239], v199 offset:18560
	ds_read_b128 v[240:243], v200 offset:12416
	ds_read_b128 v[244:247], v200 offset:18560
	s_waitcnt lgkmcnt(0)
	v_mfma_f32_32x32x16_bf16 v[96:111], v[80:83], v[136:139], 0
	v_exp_f32_e32 v151, v65
	v_exp_f32_e32 v152, v48
	v_exp_f32_e32 v153, v49
	v_exp_f32_e32 v167, v50
	v_exp_f32_e32 v169, v51
	v_exp_f32_e32 v201, v69
	v_exp_f32_e32 v208, v52
	v_mfma_f32_32x32x16_bf16 v[80:95], v[84:87], v[136:139], 0
	v_exp_f32_e32 v209, v55
	v_exp_f32_e32 v219, v74
	v_mfma_f32_32x32x16_bf16 v[96:111], v[154:157], v[132:135], v[96:111]
	v_exp_f32_e32 v155, v66
	v_exp_f32_e32 v156, v67
	v_exp_f32_e32 v157, v68
	v_mfma_f32_32x32x16_bf16 v[96:111], v[212:215], v[128:131], v[96:111]
	v_exp_f32_e32 v212, v72
	v_exp_f32_e32 v213, v73
	v_exp_f32_e32 v214, v56
	v_exp_f32_e32 v215, v57
	v_mfma_f32_32x32x16_bf16 v[96:111], v[224:227], v[124:127], v[96:111]
	v_exp_f32_e32 v224, v77
	v_exp_f32_e32 v225, v60
	v_exp_f32_e32 v226, v61
	v_exp_f32_e32 v227, v78
	v_mfma_f32_32x32x16_bf16 v[96:111], v[232:235], v[120:123], v[96:111]
	v_mfma_f32_32x32x16_bf16 v[96:111], v[240:243], v[116:119], v[96:111]
	v_mfma_f32_32x32x16_bf16 v[80:95], v[202:205], v[132:135], v[80:95]
	v_exp_f32_e32 v202, v53
	v_exp_f32_e32 v203, v70
	v_exp_f32_e32 v204, v71
	v_exp_f32_e32 v205, v54
	v_mfma_f32_32x32x16_bf16 v[80:95], v[220:223], v[128:131], v[80:95]
	v_exp_f32_e32 v220, v75
	v_exp_f32_e32 v221, v58
	v_exp_f32_e32 v222, v59
	v_exp_f32_e32 v223, v76
	v_mfma_f32_32x32x16_bf16 v[80:95], v[228:231], v[124:127], v[80:95]
	v_exp_f32_e32 v228, v79
	v_exp_f32_e32 v229, v62
	v_exp_f32_e32 v230, v63
	v_mfma_f32_32x32x16_bf16 v[80:95], v[236:239], v[120:123], v[80:95]
	ds_read_b128 v[48:51], v173 offset:49152
	ds_read_b128 v[52:55], v173 offset:53248
	ds_read_b128 v[56:59], v197 offset:49152
	ds_read_b128 v[60:63], v197 offset:53248
	ds_read_b128 v[64:67], v193 offset:49152
	ds_read_b128 v[68:71], v193 offset:53248
	ds_read_b128 v[72:75], v195 offset:49152
	ds_read_b128 v[76:79], v195 offset:53248
	v_add_f32_e32 v32, v32, v150
	v_add_f32_e32 v33, v33, v151
	v_cvt_pk_bf16_f32 v154, v150, v151
	v_add_f32_e32 v34, v34, v155
	v_add_f32_e32 v35, v35, v156
	v_cvt_pk_bf16_f32 v155, v155, v156
	v_add_f32_e32 v32, v32, v157
	v_add_f32_e32 v33, v33, v201
	v_cvt_pk_bf16_f32 v156, v157, v201
	v_add_f32_e32 v34, v34, v203
	v_add_f32_e32 v35, v35, v204
	v_cvt_pk_bf16_f32 v157, v203, v204
	v_mfma_f32_32x32x16_bf16 v[80:95], v[244:247], v[116:119], v[80:95]
	s_and_b64 vcc, exec, s[6:7]
	s_waitcnt lgkmcnt(0)
	v_mfma_f32_32x32x16_bf16 v[16:31], v[52:55], v[154:157], v[16:31]
	v_mfma_f32_32x32x16_bf16 v[0:15], v[48:51], v[154:157], v[0:15]
	v_add_f32_e32 v32, v32, v212
	v_add_f32_e32 v33, v33, v213
	v_cvt_pk_bf16_f32 v48, v212, v213
	v_add_f32_e32 v34, v34, v219
	v_add_f32_e32 v35, v35, v220
	v_cvt_pk_bf16_f32 v49, v219, v220
	v_add_f32_e32 v32, v32, v223
	v_add_f32_e32 v33, v33, v224
	v_cvt_pk_bf16_f32 v50, v223, v224
	v_cvt_pk_bf16_f32 v51, v227, v228
	v_add_f32_e32 v34, v34, v227
	v_add_f32_e32 v35, v35, v228
	v_mfma_f32_32x32x16_bf16 v[16:31], v[60:63], v[48:51], v[16:31]
	v_mfma_f32_32x32x16_bf16 v[0:15], v[56:59], v[48:51], v[0:15]
	v_add_f32_e32 v32, v32, v152
	v_add_f32_e32 v33, v33, v153
	v_cvt_pk_bf16_f32 v52, v152, v153
	v_add_f32_e32 v34, v34, v167
	v_add_f32_e32 v35, v35, v169
	v_cvt_pk_bf16_f32 v53, v167, v169
	v_add_f32_e32 v32, v32, v208
	v_add_f32_e32 v33, v33, v202
	v_cvt_pk_bf16_f32 v54, v208, v202
	v_cvt_pk_bf16_f32 v55, v205, v209
	v_add_f32_e32 v34, v34, v205
	v_add_f32_e32 v35, v35, v209
	v_mfma_f32_32x32x16_bf16 v[16:31], v[68:71], v[52:55], v[16:31]
	v_mfma_f32_32x32x16_bf16 v[0:15], v[64:67], v[52:55], v[0:15]
	v_add_f32_e32 v32, v32, v214
	v_add_f32_e32 v33, v33, v215
	v_cvt_pk_bf16_f32 v48, v214, v215
	v_add_f32_e32 v34, v34, v221
	v_add_f32_e32 v35, v35, v222
	v_cvt_pk_bf16_f32 v49, v221, v222
	v_add_f32_e32 v32, v32, v225
	v_add_f32_e32 v33, v33, v226
	v_cvt_pk_bf16_f32 v50, v225, v226
	v_cvt_pk_bf16_f32 v51, v229, v230
	v_add_f32_e32 v34, v34, v229
	v_add_f32_e32 v35, v35, v230
	v_mfma_f32_32x32x16_bf16 v[16:31], v[76:79], v[48:51], v[16:31]
	v_mfma_f32_32x32x16_bf16 v[0:15], v[72:75], v[48:51], v[0:15]
	s_cbranch_vccnz .LBB0_1196
	v_pk_add_f32 v[102:103], v[102:103], v[172:173] op_sel_hi:[1,0] neg_lo:[0,1] neg_hi:[0,1]
	v_pk_add_f32 v[110:111], v[110:111], v[172:173] op_sel_hi:[1,0] neg_lo:[0,1] neg_hi:[0,1]
	v_pk_add_f32 v[96:97], v[96:97], v[172:173] op_sel_hi:[1,0] neg_lo:[0,1] neg_hi:[0,1]
	v_pk_add_f32 v[98:99], v[98:99], v[172:173] op_sel_hi:[1,0] neg_lo:[0,1] neg_hi:[0,1]
	v_pk_add_f32 v[100:101], v[100:101], v[172:173] op_sel_hi:[1,0] neg_lo:[0,1] neg_hi:[0,1]
	v_pk_add_f32 v[104:105], v[104:105], v[172:173] op_sel_hi:[1,0] neg_lo:[0,1] neg_hi:[0,1]
	v_pk_add_f32 v[106:107], v[106:107], v[172:173] op_sel_hi:[1,0] neg_lo:[0,1] neg_hi:[0,1]
	v_pk_add_f32 v[108:109], v[108:109], v[172:173] op_sel_hi:[1,0] neg_lo:[0,1] neg_hi:[0,1]
	v_pk_add_f32 v[94:95], v[94:95], v[172:173] op_sel_hi:[1,0] neg_lo:[0,1] neg_hi:[0,1]
	v_max_f32_e32 v50, v102, v103
	v_max_f32_e32 v53, v110, v111
	v_pk_add_f32 v[82:83], v[82:83], v[172:173] op_sel_hi:[1,0] neg_lo:[0,1] neg_hi:[0,1]
	v_pk_add_f32 v[86:87], v[86:87], v[172:173] op_sel_hi:[1,0] neg_lo:[0,1] neg_hi:[0,1]
	v_pk_add_f32 v[88:89], v[88:89], v[172:173] op_sel_hi:[1,0] neg_lo:[0,1] neg_hi:[0,1]
	v_pk_add_f32 v[90:91], v[90:91], v[172:173] op_sel_hi:[1,0] neg_lo:[0,1] neg_hi:[0,1]
	v_pk_add_f32 v[92:93], v[92:93], v[172:173] op_sel_hi:[1,0] neg_lo:[0,1] neg_hi:[0,1]
	v_max_f32_e32 v48, v96, v97
	v_max_f32_e32 v49, v98, v99
	v_max3_f32 v50, v100, v101, v50
	v_max_f32_e32 v51, v104, v105
	v_max_f32_e32 v52, v106, v107
	v_max3_f32 v53, v108, v109, v53
	v_max_f32_e32 v54, v94, v95
	v_pk_add_f32 v[80:81], v[80:81], v[172:173] op_sel_hi:[1,0] neg_lo:[0,1] neg_hi:[0,1]
	v_pk_add_f32 v[84:85], v[84:85], v[172:173] op_sel_hi:[1,0] neg_lo:[0,1] neg_hi:[0,1]
	v_max3_f32 v48, v48, v49, v50
	v_max3_f32 v49, v51, v52, v53
	v_max_f32_e32 v50, v82, v83
	v_max_f32_e32 v51, v86, v87
	v_max_f32_e32 v52, v88, v89
	v_max_f32_e32 v53, v90, v91
	v_max3_f32 v54, v92, v93, v54
	v_max3_f32 v50, v80, v81, v50
	v_max3_f32 v51, v84, v85, v51
	v_max3_f32 v52, v52, v53, v54
	v_max3_f32 v50, v50, v51, v52
	v_max3_f32 v48, v48, v49, v50
	ds_bpermute_b32 v49, v218, v48
	s_mov_b32 s14, 0x41000000
	s_waitcnt lgkmcnt(0)
	v_max_f32_e32 v49, v49, v49
	v_max_f32_e32 v48, v48, v49
	v_cmp_lt_f32_e32 vcc, s14, v48
	s_cbranch_vccz .LBB0_1196
	v_max_f32_e32 v48, v48, v48
	v_max_f32_e32 v49, 0, v48
	v_exp_f32_e64 v48, -v49
	v_sub_f32_e32 v96, v96, v49
	v_sub_f32_e32 v97, v97, v49
	v_sub_f32_e32 v98, v98, v49
	v_sub_f32_e32 v99, v99, v49
	v_sub_f32_e32 v100, v100, v49
	v_sub_f32_e32 v101, v101, v49
	v_sub_f32_e32 v102, v102, v49
	v_sub_f32_e32 v103, v103, v49
	v_sub_f32_e32 v104, v104, v49
	v_sub_f32_e32 v105, v105, v49
	v_sub_f32_e32 v106, v106, v49
	v_sub_f32_e32 v107, v107, v49
	v_sub_f32_e32 v108, v108, v49
	v_sub_f32_e32 v109, v109, v49
	v_sub_f32_e32 v110, v110, v49
	v_sub_f32_e32 v111, v111, v49
	v_sub_f32_e32 v80, v80, v49
	v_sub_f32_e32 v81, v81, v49
	v_sub_f32_e32 v82, v82, v49
	v_sub_f32_e32 v83, v83, v49
	v_sub_f32_e32 v84, v84, v49
	v_sub_f32_e32 v85, v85, v49
	v_sub_f32_e32 v86, v86, v49
	v_sub_f32_e32 v87, v87, v49
	v_sub_f32_e32 v88, v88, v49
	v_sub_f32_e32 v89, v89, v49
	v_sub_f32_e32 v90, v90, v49
	v_sub_f32_e32 v91, v91, v49
	v_sub_f32_e32 v92, v92, v49
	v_sub_f32_e32 v93, v93, v49
	v_sub_f32_e32 v94, v94, v49
	v_sub_f32_e32 v95, v95, v49
	v_pk_mul_f32 v[14:15], v[14:15], v[48:49] op_sel_hi:[1,0]
	v_pk_mul_f32 v[12:13], v[12:13], v[48:49] op_sel_hi:[1,0]
	v_pk_mul_f32 v[10:11], v[10:11], v[48:49] op_sel_hi:[1,0]
	v_pk_mul_f32 v[8:9], v[8:9], v[48:49] op_sel_hi:[1,0]
	v_pk_mul_f32 v[6:7], v[6:7], v[48:49] op_sel_hi:[1,0]
	v_pk_mul_f32 v[4:5], v[4:5], v[48:49] op_sel_hi:[1,0]
	v_pk_mul_f32 v[2:3], v[2:3], v[48:49] op_sel_hi:[1,0]
	v_pk_mul_f32 v[0:1], v[0:1], v[48:49] op_sel_hi:[1,0]
	v_pk_mul_f32 v[30:31], v[30:31], v[48:49] op_sel_hi:[1,0]
	v_pk_mul_f32 v[28:29], v[28:29], v[48:49] op_sel_hi:[1,0]
	v_pk_mul_f32 v[26:27], v[26:27], v[48:49] op_sel_hi:[1,0]
	v_pk_mul_f32 v[24:25], v[24:25], v[48:49] op_sel_hi:[1,0]
	v_pk_mul_f32 v[22:23], v[22:23], v[48:49] op_sel_hi:[1,0]
	v_pk_mul_f32 v[20:21], v[20:21], v[48:49] op_sel_hi:[1,0]
	v_pk_mul_f32 v[18:19], v[18:19], v[48:49] op_sel_hi:[1,0]
	v_pk_mul_f32 v[16:17], v[16:17], v[48:49] op_sel_hi:[1,0]
	v_pk_mul_f32 v[46:47], v[46:47], v[48:49] op_sel_hi:[1,0]
	v_pk_mul_f32 v[44:45], v[44:45], v[48:49] op_sel_hi:[1,0]
	v_pk_mul_f32 v[42:43], v[42:43], v[48:49] op_sel_hi:[1,0]
	v_pk_mul_f32 v[40:41], v[40:41], v[48:49] op_sel_hi:[1,0]
	v_pk_mul_f32 v[38:39], v[38:39], v[48:49] op_sel_hi:[1,0]
	v_pk_mul_f32 v[36:37], v[36:37], v[48:49] op_sel_hi:[1,0]
	v_pk_mul_f32 v[34:35], v[34:35], v[48:49] op_sel_hi:[1,0]
	v_pk_mul_f32 v[32:33], v[32:33], v[48:49] op_sel_hi:[1,0]
	v_add_f32_e32 v172, v172, v49
.LBB0_1196:
	ds_read_b128 v[48:51], v199 offset:24576
	ds_read_b128 v[52:55], v199 offset:30720
	ds_read_b128 v[154:157], v200 offset:24576
	ds_read_b128 v[202:205], v200 offset:30720
	ds_read_b128 v[212:215], v199 offset:24640
	ds_read_b128 v[220:223], v199 offset:30784
	ds_read_b128 v[224:227], v200 offset:24640
	ds_read_b128 v[228:231], v200 offset:30784
	ds_read_b128 v[232:235], v199 offset:24704
	ds_read_b128 v[236:239], v199 offset:30848
	ds_read_b128 v[240:243], v200 offset:24704
	ds_read_b128 v[244:247], v200 offset:30848
	s_waitcnt lgkmcnt(0)
	v_mfma_f32_32x32x16_bf16 v[64:79], v[48:51], v[136:139], 0
	v_exp_f32_e32 v150, v96
	v_exp_f32_e32 v151, v97
	v_exp_f32_e32 v152, v80
	v_exp_f32_e32 v153, v81
	v_exp_f32_e32 v167, v82
	v_exp_f32_e32 v169, v83
	v_exp_f32_e32 v201, v101
	v_mfma_f32_32x32x16_bf16 v[48:63], v[52:55], v[136:139], 0
	v_exp_f32_e32 v208, v84
	v_exp_f32_e32 v209, v87
	v_exp_f32_e32 v219, v106
	v_mfma_f32_32x32x16_bf16 v[64:79], v[154:157], v[132:135], v[64:79]
	v_exp_f32_e32 v155, v98
	v_exp_f32_e32 v156, v99
	v_exp_f32_e32 v157, v100
	v_mfma_f32_32x32x16_bf16 v[64:79], v[212:215], v[128:131], v[64:79]
	v_exp_f32_e32 v212, v104
	v_exp_f32_e32 v213, v105
	v_exp_f32_e32 v214, v88
	v_exp_f32_e32 v215, v89
	v_mfma_f32_32x32x16_bf16 v[64:79], v[224:227], v[124:127], v[64:79]
	v_exp_f32_e32 v224, v109
	v_exp_f32_e32 v225, v92
	v_exp_f32_e32 v226, v93
	v_exp_f32_e32 v227, v110
	v_mfma_f32_32x32x16_bf16 v[64:79], v[232:235], v[120:123], v[64:79]
	v_mfma_f32_32x32x16_bf16 v[64:79], v[240:243], v[116:119], v[64:79]
	v_mfma_f32_32x32x16_bf16 v[48:63], v[202:205], v[132:135], v[48:63]
	v_exp_f32_e32 v202, v85
	v_exp_f32_e32 v203, v102
	v_exp_f32_e32 v204, v103
	v_exp_f32_e32 v205, v86
	v_mfma_f32_32x32x16_bf16 v[48:63], v[220:223], v[128:131], v[48:63]
	v_exp_f32_e32 v220, v107
	v_exp_f32_e32 v221, v90
	v_exp_f32_e32 v222, v91
	v_exp_f32_e32 v223, v108
	v_mfma_f32_32x32x16_bf16 v[48:63], v[228:231], v[124:127], v[48:63]
	v_exp_f32_e32 v228, v111
	v_exp_f32_e32 v229, v94
	v_exp_f32_e32 v230, v95
	v_mfma_f32_32x32x16_bf16 v[48:63], v[236:239], v[120:123], v[48:63]
	ds_read_b128 v[80:83], v173 offset:57344
	ds_read_b128 v[84:87], v173 offset:61440
	ds_read_b128 v[88:91], v197 offset:57344
	ds_read_b128 v[92:95], v197 offset:61440
	ds_read_b128 v[96:99], v193 offset:57344
	ds_read_b128 v[100:103], v193 offset:61440
	ds_read_b128 v[104:107], v195 offset:57344
	ds_read_b128 v[108:111], v195 offset:61440
	v_add_f32_e32 v32, v32, v150
	v_add_f32_e32 v33, v33, v151
	v_cvt_pk_bf16_f32 v154, v150, v151
	v_add_f32_e32 v34, v34, v155
	v_add_f32_e32 v35, v35, v156
	v_cvt_pk_bf16_f32 v155, v155, v156
	v_add_f32_e32 v32, v32, v157
	v_add_f32_e32 v33, v33, v201
	v_cvt_pk_bf16_f32 v156, v157, v201
	v_add_f32_e32 v34, v34, v203
	v_add_f32_e32 v35, v35, v204
	v_cvt_pk_bf16_f32 v157, v203, v204
	v_mfma_f32_32x32x16_bf16 v[48:63], v[244:247], v[116:119], v[48:63]
	s_cmp_eq_u32 s64, 0
	s_cbranch_scc1 .Lmla_late_skip0
	s_waitcnt vmcnt(0)
	s_barrier
.Lmla_late_skip0:
	s_and_b64 vcc, exec, s[6:7]
	s_waitcnt lgkmcnt(0)
	v_mfma_f32_32x32x16_bf16 v[16:31], v[84:87], v[154:157], v[16:31]
	v_mfma_f32_32x32x16_bf16 v[0:15], v[80:83], v[154:157], v[0:15]
	v_add_f32_e32 v32, v32, v212
	v_add_f32_e32 v33, v33, v213
	v_cvt_pk_bf16_f32 v80, v212, v213
	v_add_f32_e32 v34, v34, v219
	v_add_f32_e32 v35, v35, v220
	v_cvt_pk_bf16_f32 v81, v219, v220
	v_add_f32_e32 v32, v32, v223
	v_add_f32_e32 v33, v33, v224
	v_cvt_pk_bf16_f32 v82, v223, v224
	v_cvt_pk_bf16_f32 v83, v227, v228
	v_add_f32_e32 v34, v34, v227
	v_add_f32_e32 v35, v35, v228
	v_mfma_f32_32x32x16_bf16 v[16:31], v[92:95], v[80:83], v[16:31]
	v_mfma_f32_32x32x16_bf16 v[0:15], v[88:91], v[80:83], v[0:15]
	v_add_f32_e32 v32, v32, v152
	v_add_f32_e32 v33, v33, v153
	v_cvt_pk_bf16_f32 v84, v152, v153
	v_add_f32_e32 v34, v34, v167
	v_add_f32_e32 v35, v35, v169
	v_cvt_pk_bf16_f32 v85, v167, v169
	v_add_f32_e32 v32, v32, v208
	v_add_f32_e32 v33, v33, v202
	v_cvt_pk_bf16_f32 v86, v208, v202
	v_cvt_pk_bf16_f32 v87, v205, v209
	v_add_f32_e32 v34, v34, v205
	v_add_f32_e32 v35, v35, v209
	v_mfma_f32_32x32x16_bf16 v[16:31], v[100:103], v[84:87], v[16:31]
	v_mfma_f32_32x32x16_bf16 v[0:15], v[96:99], v[84:87], v[0:15]
	v_add_f32_e32 v32, v32, v214
	v_add_f32_e32 v33, v33, v215
	v_cvt_pk_bf16_f32 v80, v214, v215
	v_add_f32_e32 v34, v34, v221
	v_add_f32_e32 v35, v35, v222
	v_cvt_pk_bf16_f32 v81, v221, v222
	v_add_f32_e32 v32, v32, v225
	v_add_f32_e32 v33, v33, v226
	v_cvt_pk_bf16_f32 v82, v225, v226
	v_cvt_pk_bf16_f32 v83, v229, v230
	v_add_f32_e32 v34, v34, v229
	v_add_f32_e32 v35, v35, v230
	v_mfma_f32_32x32x16_bf16 v[16:31], v[108:111], v[80:83], v[16:31]
	v_mfma_f32_32x32x16_bf16 v[0:15], v[104:107], v[80:83], v[0:15]
	s_cbranch_vccnz .LBB0_1199
	v_pk_add_f32 v[70:71], v[70:71], v[172:173] op_sel_hi:[1,0] neg_lo:[0,1] neg_hi:[0,1]
	v_pk_add_f32 v[78:79], v[78:79], v[172:173] op_sel_hi:[1,0] neg_lo:[0,1] neg_hi:[0,1]
	v_pk_add_f32 v[64:65], v[64:65], v[172:173] op_sel_hi:[1,0] neg_lo:[0,1] neg_hi:[0,1]
	v_pk_add_f32 v[66:67], v[66:67], v[172:173] op_sel_hi:[1,0] neg_lo:[0,1] neg_hi:[0,1]
	v_pk_add_f32 v[68:69], v[68:69], v[172:173] op_sel_hi:[1,0] neg_lo:[0,1] neg_hi:[0,1]
	v_pk_add_f32 v[72:73], v[72:73], v[172:173] op_sel_hi:[1,0] neg_lo:[0,1] neg_hi:[0,1]
	v_pk_add_f32 v[74:75], v[74:75], v[172:173] op_sel_hi:[1,0] neg_lo:[0,1] neg_hi:[0,1]
	v_pk_add_f32 v[76:77], v[76:77], v[172:173] op_sel_hi:[1,0] neg_lo:[0,1] neg_hi:[0,1]
	v_pk_add_f32 v[62:63], v[62:63], v[172:173] op_sel_hi:[1,0] neg_lo:[0,1] neg_hi:[0,1]
	v_max_f32_e32 v82, v70, v71
	v_max_f32_e32 v85, v78, v79
	v_pk_add_f32 v[50:51], v[50:51], v[172:173] op_sel_hi:[1,0] neg_lo:[0,1] neg_hi:[0,1]
	v_pk_add_f32 v[54:55], v[54:55], v[172:173] op_sel_hi:[1,0] neg_lo:[0,1] neg_hi:[0,1]
	v_pk_add_f32 v[56:57], v[56:57], v[172:173] op_sel_hi:[1,0] neg_lo:[0,1] neg_hi:[0,1]
	v_pk_add_f32 v[58:59], v[58:59], v[172:173] op_sel_hi:[1,0] neg_lo:[0,1] neg_hi:[0,1]
	v_pk_add_f32 v[60:61], v[60:61], v[172:173] op_sel_hi:[1,0] neg_lo:[0,1] neg_hi:[0,1]
	v_max_f32_e32 v80, v64, v65
	v_max_f32_e32 v81, v66, v67
	v_max3_f32 v82, v68, v69, v82
	v_max_f32_e32 v83, v72, v73
	v_max_f32_e32 v84, v74, v75
	v_max3_f32 v85, v76, v77, v85
	v_max_f32_e32 v86, v62, v63
	v_pk_add_f32 v[48:49], v[48:49], v[172:173] op_sel_hi:[1,0] neg_lo:[0,1] neg_hi:[0,1]
	v_pk_add_f32 v[52:53], v[52:53], v[172:173] op_sel_hi:[1,0] neg_lo:[0,1] neg_hi:[0,1]
	v_max3_f32 v80, v80, v81, v82
	v_max3_f32 v81, v83, v84, v85
	v_max_f32_e32 v82, v50, v51
	v_max_f32_e32 v83, v54, v55
	v_max_f32_e32 v84, v56, v57
	v_max_f32_e32 v85, v58, v59
	v_max3_f32 v86, v60, v61, v86
	v_max3_f32 v82, v48, v49, v82
	v_max3_f32 v83, v52, v53, v83
	v_max3_f32 v84, v84, v85, v86
	v_max3_f32 v82, v82, v83, v84
	v_max3_f32 v80, v80, v81, v82
	ds_bpermute_b32 v81, v218, v80
	s_mov_b32 s14, 0x41000000
	s_waitcnt lgkmcnt(0)
	v_max_f32_e32 v81, v81, v81
	v_max_f32_e32 v80, v80, v81
	v_cmp_lt_f32_e32 vcc, s14, v80
	s_cbranch_vccz .LBB0_1199
	v_max_f32_e32 v80, v80, v80
	v_max_f32_e32 v81, 0, v80
	v_exp_f32_e64 v80, -v81
	v_sub_f32_e32 v64, v64, v81
	v_sub_f32_e32 v65, v65, v81
	v_sub_f32_e32 v66, v66, v81
	v_sub_f32_e32 v67, v67, v81
	v_sub_f32_e32 v68, v68, v81
	v_sub_f32_e32 v69, v69, v81
	v_sub_f32_e32 v70, v70, v81
	v_sub_f32_e32 v71, v71, v81
	v_sub_f32_e32 v72, v72, v81
	v_sub_f32_e32 v73, v73, v81
	v_sub_f32_e32 v74, v74, v81
	v_sub_f32_e32 v75, v75, v81
	v_sub_f32_e32 v76, v76, v81
	v_sub_f32_e32 v77, v77, v81
	v_sub_f32_e32 v78, v78, v81
	v_sub_f32_e32 v79, v79, v81
	v_sub_f32_e32 v48, v48, v81
	v_sub_f32_e32 v49, v49, v81
	v_sub_f32_e32 v50, v50, v81
	v_sub_f32_e32 v51, v51, v81
	v_sub_f32_e32 v52, v52, v81
	v_sub_f32_e32 v53, v53, v81
	v_sub_f32_e32 v54, v54, v81
	v_sub_f32_e32 v55, v55, v81
	v_sub_f32_e32 v56, v56, v81
	v_sub_f32_e32 v57, v57, v81
	v_sub_f32_e32 v58, v58, v81
	v_sub_f32_e32 v59, v59, v81
	v_sub_f32_e32 v60, v60, v81
	v_sub_f32_e32 v61, v61, v81
	v_sub_f32_e32 v62, v62, v81
	v_sub_f32_e32 v63, v63, v81
	v_pk_mul_f32 v[14:15], v[14:15], v[80:81] op_sel_hi:[1,0]
	v_pk_mul_f32 v[12:13], v[12:13], v[80:81] op_sel_hi:[1,0]
	v_pk_mul_f32 v[10:11], v[10:11], v[80:81] op_sel_hi:[1,0]
	v_pk_mul_f32 v[8:9], v[8:9], v[80:81] op_sel_hi:[1,0]
	v_pk_mul_f32 v[6:7], v[6:7], v[80:81] op_sel_hi:[1,0]
	v_pk_mul_f32 v[4:5], v[4:5], v[80:81] op_sel_hi:[1,0]
	v_pk_mul_f32 v[2:3], v[2:3], v[80:81] op_sel_hi:[1,0]
	v_pk_mul_f32 v[0:1], v[0:1], v[80:81] op_sel_hi:[1,0]
	v_pk_mul_f32 v[30:31], v[30:31], v[80:81] op_sel_hi:[1,0]
	v_pk_mul_f32 v[28:29], v[28:29], v[80:81] op_sel_hi:[1,0]
	v_pk_mul_f32 v[26:27], v[26:27], v[80:81] op_sel_hi:[1,0]
	v_pk_mul_f32 v[24:25], v[24:25], v[80:81] op_sel_hi:[1,0]
	v_pk_mul_f32 v[22:23], v[22:23], v[80:81] op_sel_hi:[1,0]
	v_pk_mul_f32 v[20:21], v[20:21], v[80:81] op_sel_hi:[1,0]
	v_pk_mul_f32 v[18:19], v[18:19], v[80:81] op_sel_hi:[1,0]
	v_pk_mul_f32 v[16:17], v[16:17], v[80:81] op_sel_hi:[1,0]
	v_pk_mul_f32 v[46:47], v[46:47], v[80:81] op_sel_hi:[1,0]
	v_pk_mul_f32 v[44:45], v[44:45], v[80:81] op_sel_hi:[1,0]
	v_pk_mul_f32 v[42:43], v[42:43], v[80:81] op_sel_hi:[1,0]
	v_pk_mul_f32 v[40:41], v[40:41], v[80:81] op_sel_hi:[1,0]
	v_pk_mul_f32 v[38:39], v[38:39], v[80:81] op_sel_hi:[1,0]
	v_pk_mul_f32 v[36:37], v[36:37], v[80:81] op_sel_hi:[1,0]
	v_pk_mul_f32 v[34:35], v[34:35], v[80:81] op_sel_hi:[1,0]
	v_pk_mul_f32 v[32:33], v[32:33], v[80:81] op_sel_hi:[1,0]
	v_add_f32_e32 v172, v172, v81

.Lmla_early_skip0:
	s_mov_b64 s[14:15], 0xf60f000
	v_lshl_add_u64 v[80:81], v[186:187], 0, s[14:15]
	s_add_i32 m0, s52, 0x3000
	s_mov_b64 s[20:21], 0x3600200
	global_load_lds_dwordx4 v[80:81], off
	s_mov_b64 s[14:15], -1
	s_and_b64 vcc, exec, s[38:39]
	v_lshl_add_u64 v[80:81], v[188:189], 0, s[20:21]
	s_cbranch_vccz .LBB0_1201
	s_sub_i32 m0, s60, s66
	s_add_i32 m0, m0, 0x8000
	s_mul_i32 s48, s12, 0x3000
	global_load_lds_dwordx4 v[80:81], off
	v_lshl_add_u64 v[82:83], v[176:177], 0, s[48:49]
	v_lshl_add_u64 v[82:83], v[82:83], 0, s[42:43]
	s_mov_b64 s[14:15], 0x12000
	v_lshl_add_u64 v[82:83], v[82:83], 0, s[14:15]
	s_mov_b64 s[14:15], 0
.LBB0_1201:
	s_andn2_b64 vcc, exec, s[14:15]
	s_mov_b32 s14, s54
	s_cbranch_vccnz .LBB0_1203
	s_mov_b64 s[14:15], 0xf60f000
	v_lshl_add_u64 v[82:83], v[190:191], 0, s[14:15]
	s_add_i32 m0, s53, 0x3000
	s_mov_b64 s[14:15], 0xf612000
	global_load_lds_dwordx4 v[82:83], off
	s_sub_i32 m0, s60, s66
	s_add_i32 m0, m0, 0x8000
	v_lshl_add_u64 v[82:83], v[190:191], 0, s[14:15]
	global_load_lds_dwordx4 v[80:81], off
	v_lshl_add_u64 v[80:81], v[186:187], 0, s[14:15]
	s_add_i32 m0, s52, 0x6000
	s_mov_b32 s14, s55
	global_load_lds_dwordx4 v[80:81], off
.LBB0_1203:
	s_mov_b32 m0, s14
	s_mov_b64 s[14:15], 0x3600280
	global_load_lds_dwordx4 v[82:83], off
	v_lshl_add_u64 v[80:81], v[188:189], 0, s[14:15]
	s_sub_i32 m0, s62, s66
	s_add_i32 m0, m0, 0x8000
	v_exp_f32_e32 v150, v64
	global_load_lds_dwordx4 v[80:81], off
	ds_read_b128 v[80:83], v199 offset:36864
	ds_read_b128 v[84:87], v199 offset:43008
	ds_read_b128 v[154:157], v200 offset:36864
	ds_read_b128 v[186:189], v200 offset:43008
	ds_read_b128 v[202:205], v199 offset:36928
	ds_read_b128 v[212:215], v199 offset:43072
	ds_read_b128 v[220:223], v200 offset:36928
	ds_read_b128 v[224:227], v200 offset:43072
	ds_read_b128 v[228:231], v199 offset:36992
	ds_read_b128 v[232:235], v199 offset:43136
	ds_read_b128 v[236:239], v200 offset:36992
	ds_read_b128 v[240:243], v200 offset:43136
	s_waitcnt lgkmcnt(0)
	v_mfma_f32_32x32x16_bf16 v[96:111], v[80:83], v[136:139], 0
	v_exp_f32_e32 v151, v65
	v_exp_f32_e32 v152, v48
	v_exp_f32_e32 v153, v49
	v_exp_f32_e32 v167, v50
	v_exp_f32_e32 v169, v51
	v_exp_f32_e32 v190, v69
	v_exp_f32_e32 v191, v52
	v_mfma_f32_32x32x16_bf16 v[80:95], v[84:87], v[136:139], 0
	v_exp_f32_e32 v201, v55
	v_exp_f32_e32 v208, v74
	v_exp_f32_e32 v209, v75
	v_exp_f32_e32 v219, v60
	v_mfma_f32_32x32x16_bf16 v[96:111], v[154:157], v[132:135], v[96:111]
	v_exp_f32_e32 v155, v66
	v_exp_f32_e32 v156, v67
	v_exp_f32_e32 v157, v68
	v_mfma_f32_32x32x16_bf16 v[96:111], v[202:205], v[128:131], v[96:111]
	v_exp_f32_e32 v202, v72
	v_exp_f32_e32 v203, v73
	v_exp_f32_e32 v204, v56
	v_exp_f32_e32 v205, v57
	v_mfma_f32_32x32x16_bf16 v[96:111], v[220:223], v[124:127], v[96:111]
	v_exp_f32_e32 v220, v61
	v_exp_f32_e32 v221, v78
	v_exp_f32_e32 v222, v79
	v_exp_f32_e32 v223, v62
	v_mfma_f32_32x32x16_bf16 v[96:111], v[228:231], v[120:123], v[96:111]
	v_mfma_f32_32x32x16_bf16 v[96:111], v[236:239], v[116:119], v[96:111]
	v_mfma_f32_32x32x16_bf16 v[80:95], v[186:189], v[132:135], v[80:95]
	v_exp_f32_e32 v186, v53
	v_exp_f32_e32 v187, v70
	v_exp_f32_e32 v188, v71
	v_exp_f32_e32 v189, v54
	v_mfma_f32_32x32x16_bf16 v[80:95], v[212:215], v[128:131], v[80:95]
	v_exp_f32_e32 v212, v58
	v_exp_f32_e32 v213, v59
	v_exp_f32_e32 v214, v76
	v_exp_f32_e32 v215, v77
	v_mfma_f32_32x32x16_bf16 v[80:95], v[224:227], v[124:127], v[80:95]
	v_exp_f32_e32 v224, v63
	v_mfma_f32_32x32x16_bf16 v[80:95], v[232:235], v[120:123], v[80:95]
	ds_read_b128 v[48:51], v192 offset:16384
	ds_read_b128 v[52:55], v192 offset:20480
	ds_read_b128 v[56:59], v198 offset:16384
	ds_read_b128 v[60:63], v198 offset:20480
	ds_read_b128 v[64:67], v194 offset:16384
	ds_read_b128 v[68:71], v194 offset:20480
	ds_read_b128 v[72:75], v196 offset:16384
	ds_read_b128 v[76:79], v196 offset:20480
	v_add_f32_e32 v32, v32, v150
	v_add_f32_e32 v33, v33, v151
	v_cvt_pk_bf16_f32 v154, v150, v151
	v_add_f32_e32 v34, v34, v155
	v_add_f32_e32 v35, v35, v156
	v_cvt_pk_bf16_f32 v155, v155, v156
	v_add_f32_e32 v32, v32, v157
	v_add_f32_e32 v33, v33, v190
	v_cvt_pk_bf16_f32 v156, v157, v190
	v_add_f32_e32 v34, v34, v187
	v_add_f32_e32 v35, v35, v188
	v_cvt_pk_bf16_f32 v157, v187, v188
	v_mfma_f32_32x32x16_bf16 v[80:95], v[240:243], v[116:119], v[80:95]
	s_and_b64 vcc, exec, s[6:7]
	s_waitcnt lgkmcnt(0)
	v_mfma_f32_32x32x16_bf16 v[16:31], v[52:55], v[154:157], v[16:31]
	v_mfma_f32_32x32x16_bf16 v[0:15], v[48:51], v[154:157], v[0:15]
	v_add_f32_e32 v32, v32, v202
	v_add_f32_e32 v33, v33, v203
	v_cvt_pk_bf16_f32 v48, v202, v203
	v_add_f32_e32 v34, v34, v208
	v_add_f32_e32 v35, v35, v209
	v_cvt_pk_bf16_f32 v49, v208, v209
	v_add_f32_e32 v32, v32, v214
	v_add_f32_e32 v33, v33, v215
	v_cvt_pk_bf16_f32 v50, v214, v215
	v_cvt_pk_bf16_f32 v51, v221, v222
	v_add_f32_e32 v34, v34, v221
	v_add_f32_e32 v35, v35, v222
	v_mfma_f32_32x32x16_bf16 v[16:31], v[60:63], v[48:51], v[16:31]
	v_mfma_f32_32x32x16_bf16 v[0:15], v[56:59], v[48:51], v[0:15]
	v_add_f32_e32 v32, v32, v152
	v_add_f32_e32 v33, v33, v153
	v_cvt_pk_bf16_f32 v52, v152, v153
	v_add_f32_e32 v34, v34, v167
	v_add_f32_e32 v35, v35, v169
	v_cvt_pk_bf16_f32 v53, v167, v169
	v_add_f32_e32 v32, v32, v191
	v_add_f32_e32 v33, v33, v186
	v_cvt_pk_bf16_f32 v54, v191, v186
	v_cvt_pk_bf16_f32 v55, v189, v201
	v_add_f32_e32 v34, v34, v189
	v_add_f32_e32 v35, v35, v201
	v_mfma_f32_32x32x16_bf16 v[16:31], v[68:71], v[52:55], v[16:31]
	v_mfma_f32_32x32x16_bf16 v[0:15], v[64:67], v[52:55], v[0:15]
	v_add_f32_e32 v32, v32, v204
	v_add_f32_e32 v33, v33, v205
	v_cvt_pk_bf16_f32 v48, v204, v205
	v_add_f32_e32 v34, v34, v212
	v_add_f32_e32 v35, v35, v213
	v_cvt_pk_bf16_f32 v49, v212, v213
	v_add_f32_e32 v32, v32, v219
	v_add_f32_e32 v33, v33, v220
	v_cvt_pk_bf16_f32 v50, v219, v220
	v_cvt_pk_bf16_f32 v51, v223, v224
	v_add_f32_e32 v34, v34, v223
	v_add_f32_e32 v35, v35, v224
	v_mfma_f32_32x32x16_bf16 v[16:31], v[76:79], v[48:51], v[16:31]
	v_mfma_f32_32x32x16_bf16 v[0:15], v[72:75], v[48:51], v[0:15]
	s_cbranch_vccnz .LBB0_1206
	v_pk_add_f32 v[102:103], v[102:103], v[172:173] op_sel_hi:[1,0] neg_lo:[0,1] neg_hi:[0,1]
	v_pk_add_f32 v[110:111], v[110:111], v[172:173] op_sel_hi:[1,0] neg_lo:[0,1] neg_hi:[0,1]
	v_pk_add_f32 v[96:97], v[96:97], v[172:173] op_sel_hi:[1,0] neg_lo:[0,1] neg_hi:[0,1]
	v_pk_add_f32 v[98:99], v[98:99], v[172:173] op_sel_hi:[1,0] neg_lo:[0,1] neg_hi:[0,1]
	v_pk_add_f32 v[100:101], v[100:101], v[172:173] op_sel_hi:[1,0] neg_lo:[0,1] neg_hi:[0,1]
	v_pk_add_f32 v[104:105], v[104:105], v[172:173] op_sel_hi:[1,0] neg_lo:[0,1] neg_hi:[0,1]
	v_pk_add_f32 v[106:107], v[106:107], v[172:173] op_sel_hi:[1,0] neg_lo:[0,1] neg_hi:[0,1]
	v_pk_add_f32 v[108:109], v[108:109], v[172:173] op_sel_hi:[1,0] neg_lo:[0,1] neg_hi:[0,1]
	v_pk_add_f32 v[94:95], v[94:95], v[172:173] op_sel_hi:[1,0] neg_lo:[0,1] neg_hi:[0,1]
	v_max_f32_e32 v50, v102, v103
	v_max_f32_e32 v53, v110, v111
	v_pk_add_f32 v[82:83], v[82:83], v[172:173] op_sel_hi:[1,0] neg_lo:[0,1] neg_hi:[0,1]
	v_pk_add_f32 v[86:87], v[86:87], v[172:173] op_sel_hi:[1,0] neg_lo:[0,1] neg_hi:[0,1]
	v_pk_add_f32 v[88:89], v[88:89], v[172:173] op_sel_hi:[1,0] neg_lo:[0,1] neg_hi:[0,1]
	v_pk_add_f32 v[90:91], v[90:91], v[172:173] op_sel_hi:[1,0] neg_lo:[0,1] neg_hi:[0,1]
	v_pk_add_f32 v[92:93], v[92:93], v[172:173] op_sel_hi:[1,0] neg_lo:[0,1] neg_hi:[0,1]
	v_max_f32_e32 v48, v96, v97
	v_max_f32_e32 v49, v98, v99
	v_max3_f32 v50, v100, v101, v50
	v_max_f32_e32 v51, v104, v105
	v_max_f32_e32 v52, v106, v107
	v_max3_f32 v53, v108, v109, v53
	v_max_f32_e32 v54, v94, v95
	v_pk_add_f32 v[80:81], v[80:81], v[172:173] op_sel_hi:[1,0] neg_lo:[0,1] neg_hi:[0,1]
	v_pk_add_f32 v[84:85], v[84:85], v[172:173] op_sel_hi:[1,0] neg_lo:[0,1] neg_hi:[0,1]
	v_max3_f32 v48, v48, v49, v50
	v_max3_f32 v49, v51, v52, v53
	v_max_f32_e32 v50, v82, v83
	v_max_f32_e32 v51, v86, v87
	v_max_f32_e32 v52, v88, v89
	v_max_f32_e32 v53, v90, v91
	v_max3_f32 v54, v92, v93, v54
	v_max3_f32 v50, v80, v81, v50
	v_max3_f32 v51, v84, v85, v51
	v_max3_f32 v52, v52, v53, v54
	v_max3_f32 v50, v50, v51, v52
	v_max3_f32 v48, v48, v49, v50
	ds_bpermute_b32 v49, v218, v48
	s_mov_b32 s14, 0x41000000
	s_waitcnt lgkmcnt(0)
	v_max_f32_e32 v49, v49, v49
	v_max_f32_e32 v48, v48, v49
	v_cmp_lt_f32_e32 vcc, s14, v48
	s_cbranch_vccz .LBB0_1206
	v_max_f32_e32 v48, v48, v48
	v_max_f32_e32 v49, 0, v48
	v_exp_f32_e64 v48, -v49
	v_sub_f32_e32 v96, v96, v49
	v_sub_f32_e32 v97, v97, v49
	v_sub_f32_e32 v98, v98, v49
	v_sub_f32_e32 v99, v99, v49
	v_sub_f32_e32 v100, v100, v49
	v_sub_f32_e32 v101, v101, v49
	v_sub_f32_e32 v102, v102, v49
	v_sub_f32_e32 v103, v103, v49
	v_sub_f32_e32 v104, v104, v49
	v_sub_f32_e32 v105, v105, v49
	v_sub_f32_e32 v106, v106, v49
	v_sub_f32_e32 v107, v107, v49
	v_sub_f32_e32 v108, v108, v49
	v_sub_f32_e32 v109, v109, v49
	v_sub_f32_e32 v110, v110, v49
	v_sub_f32_e32 v111, v111, v49
	v_sub_f32_e32 v80, v80, v49
	v_sub_f32_e32 v81, v81, v49
	v_sub_f32_e32 v82, v82, v49
	v_sub_f32_e32 v83, v83, v49
	v_sub_f32_e32 v84, v84, v49
	v_sub_f32_e32 v85, v85, v49
	v_sub_f32_e32 v86, v86, v49
	v_sub_f32_e32 v87, v87, v49
	v_sub_f32_e32 v88, v88, v49
	v_sub_f32_e32 v89, v89, v49
	v_sub_f32_e32 v90, v90, v49
	v_sub_f32_e32 v91, v91, v49
	v_sub_f32_e32 v92, v92, v49
	v_sub_f32_e32 v93, v93, v49
	v_sub_f32_e32 v94, v94, v49
	v_sub_f32_e32 v95, v95, v49
	v_pk_mul_f32 v[14:15], v[14:15], v[48:49] op_sel_hi:[1,0]
	v_pk_mul_f32 v[12:13], v[12:13], v[48:49] op_sel_hi:[1,0]
	v_pk_mul_f32 v[10:11], v[10:11], v[48:49] op_sel_hi:[1,0]
	v_pk_mul_f32 v[8:9], v[8:9], v[48:49] op_sel_hi:[1,0]
	v_pk_mul_f32 v[6:7], v[6:7], v[48:49] op_sel_hi:[1,0]
	v_pk_mul_f32 v[4:5], v[4:5], v[48:49] op_sel_hi:[1,0]
	v_pk_mul_f32 v[2:3], v[2:3], v[48:49] op_sel_hi:[1,0]
	v_pk_mul_f32 v[0:1], v[0:1], v[48:49] op_sel_hi:[1,0]
	v_pk_mul_f32 v[30:31], v[30:31], v[48:49] op_sel_hi:[1,0]
	v_pk_mul_f32 v[28:29], v[28:29], v[48:49] op_sel_hi:[1,0]
	v_pk_mul_f32 v[26:27], v[26:27], v[48:49] op_sel_hi:[1,0]
	v_pk_mul_f32 v[24:25], v[24:25], v[48:49] op_sel_hi:[1,0]
	v_pk_mul_f32 v[22:23], v[22:23], v[48:49] op_sel_hi:[1,0]
	v_pk_mul_f32 v[20:21], v[20:21], v[48:49] op_sel_hi:[1,0]
	v_pk_mul_f32 v[18:19], v[18:19], v[48:49] op_sel_hi:[1,0]
	v_pk_mul_f32 v[16:17], v[16:17], v[48:49] op_sel_hi:[1,0]
	v_pk_mul_f32 v[46:47], v[46:47], v[48:49] op_sel_hi:[1,0]
	v_pk_mul_f32 v[44:45], v[44:45], v[48:49] op_sel_hi:[1,0]
	v_pk_mul_f32 v[42:43], v[42:43], v[48:49] op_sel_hi:[1,0]
	v_pk_mul_f32 v[40:41], v[40:41], v[48:49] op_sel_hi:[1,0]
	v_pk_mul_f32 v[38:39], v[38:39], v[48:49] op_sel_hi:[1,0]
	v_pk_mul_f32 v[36:37], v[36:37], v[48:49] op_sel_hi:[1,0]
	v_pk_mul_f32 v[34:35], v[34:35], v[48:49] op_sel_hi:[1,0]
	v_pk_mul_f32 v[32:33], v[32:33], v[48:49] op_sel_hi:[1,0]
	v_add_f32_e32 v172, v172, v49
.LBB0_1206:
	ds_read_b128 v[48:51], v199
	ds_read_b128 v[52:55], v199 offset:6144
	ds_read_b128 v[154:157], v200
	ds_read_b128 v[186:189], v200 offset:6144
	ds_read_b128 v[202:205], v199 offset:64
	ds_read_b128 v[212:215], v199 offset:6208
	ds_read_b128 v[220:223], v200 offset:64
	ds_read_b128 v[224:227], v200 offset:6208
	ds_read_b128 v[228:231], v199 offset:128
	ds_read_b128 v[232:235], v199 offset:6272
	ds_read_b128 v[236:239], v200 offset:128
	ds_read_b128 v[240:243], v200 offset:6272
	s_waitcnt lgkmcnt(0)
	v_mfma_f32_32x32x16_bf16 v[64:79], v[48:51], v[136:139], 0
	v_exp_f32_e32 v150, v96
	v_exp_f32_e32 v151, v97
	v_exp_f32_e32 v152, v80
	v_exp_f32_e32 v153, v81
	v_exp_f32_e32 v167, v82
	v_exp_f32_e32 v169, v83
	v_exp_f32_e32 v190, v101
	v_mfma_f32_32x32x16_bf16 v[48:63], v[52:55], v[136:139], 0
	v_exp_f32_e32 v191, v84
	v_exp_f32_e32 v201, v87
	v_exp_f32_e32 v208, v106
	v_exp_f32_e32 v209, v107
	v_exp_f32_e32 v219, v92
	v_mfma_f32_32x32x16_bf16 v[64:79], v[154:157], v[132:135], v[64:79]
	v_exp_f32_e32 v155, v98
	v_exp_f32_e32 v156, v99
	v_exp_f32_e32 v157, v100
	v_mfma_f32_32x32x16_bf16 v[64:79], v[202:205], v[128:131], v[64:79]
	v_exp_f32_e32 v202, v104
	v_exp_f32_e32 v203, v105
	v_exp_f32_e32 v204, v88
	v_exp_f32_e32 v205, v89
	v_mfma_f32_32x32x16_bf16 v[64:79], v[220:223], v[124:127], v[64:79]
	v_exp_f32_e32 v220, v93
	v_exp_f32_e32 v221, v110
	v_exp_f32_e32 v222, v111
	v_exp_f32_e32 v223, v94
	v_mfma_f32_32x32x16_bf16 v[64:79], v[228:231], v[120:123], v[64:79]
	v_mfma_f32_32x32x16_bf16 v[64:79], v[236:239], v[116:119], v[64:79]
	v_mfma_f32_32x32x16_bf16 v[48:63], v[186:189], v[132:135], v[48:63]
	v_exp_f32_e32 v186, v85
	v_exp_f32_e32 v187, v102
	v_exp_f32_e32 v188, v103
	v_exp_f32_e32 v189, v86
	v_mfma_f32_32x32x16_bf16 v[48:63], v[212:215], v[128:131], v[48:63]
	v_exp_f32_e32 v212, v90
	v_exp_f32_e32 v213, v91
	v_exp_f32_e32 v214, v108
	v_exp_f32_e32 v215, v109
	v_mfma_f32_32x32x16_bf16 v[48:63], v[224:227], v[124:127], v[48:63]
	v_exp_f32_e32 v224, v95
	v_mfma_f32_32x32x16_bf16 v[48:63], v[232:235], v[120:123], v[48:63]
	ds_read_b128 v[80:83], v192 offset:24576
	ds_read_b128 v[84:87], v192 offset:28672
	ds_read_b128 v[88:91], v198 offset:24576
	ds_read_b128 v[92:95], v198 offset:28672
	ds_read_b128 v[96:99], v194 offset:24576
	ds_read_b128 v[100:103], v194 offset:28672
	ds_read_b128 v[104:107], v196 offset:24576
	ds_read_b128 v[108:111], v196 offset:28672
	v_add_f32_e32 v32, v32, v150
	v_add_f32_e32 v33, v33, v151
	v_cvt_pk_bf16_f32 v154, v150, v151
	v_add_f32_e32 v34, v34, v155
	v_add_f32_e32 v35, v35, v156
	v_cvt_pk_bf16_f32 v155, v155, v156
	v_add_f32_e32 v32, v32, v157
	v_add_f32_e32 v33, v33, v190
	v_cvt_pk_bf16_f32 v156, v157, v190
	v_add_f32_e32 v34, v34, v187
	v_add_f32_e32 v35, v35, v188
	v_cvt_pk_bf16_f32 v157, v187, v188
	v_mfma_f32_32x32x16_bf16 v[48:63], v[240:243], v[116:119], v[48:63]
	s_cmp_eq_u32 s64, 0
	s_cbranch_scc1 .Lmla_late_skip1
	s_waitcnt vmcnt(0)
	s_barrier
.Lmla_late_skip1:
	s_and_b64 vcc, exec, s[6:7]
	s_waitcnt lgkmcnt(0)
	v_mfma_f32_32x32x16_bf16 v[16:31], v[84:87], v[154:157], v[16:31]
	v_mfma_f32_32x32x16_bf16 v[0:15], v[80:83], v[154:157], v[0:15]
	v_add_f32_e32 v32, v32, v202
	v_add_f32_e32 v33, v33, v203
	v_cvt_pk_bf16_f32 v80, v202, v203
	v_add_f32_e32 v34, v34, v208
	v_add_f32_e32 v35, v35, v209
	v_cvt_pk_bf16_f32 v81, v208, v209
	v_add_f32_e32 v32, v32, v214
	v_add_f32_e32 v33, v33, v215
	v_cvt_pk_bf16_f32 v82, v214, v215
	v_cvt_pk_bf16_f32 v83, v221, v222
	v_add_f32_e32 v34, v34, v221
	v_add_f32_e32 v35, v35, v222
	v_mfma_f32_32x32x16_bf16 v[16:31], v[92:95], v[80:83], v[16:31]
	v_mfma_f32_32x32x16_bf16 v[0:15], v[88:91], v[80:83], v[0:15]
	v_add_f32_e32 v32, v32, v152
	v_add_f32_e32 v33, v33, v153
	v_cvt_pk_bf16_f32 v84, v152, v153
	v_add_f32_e32 v34, v34, v167
	v_add_f32_e32 v35, v35, v169
	v_cvt_pk_bf16_f32 v85, v167, v169
	v_add_f32_e32 v32, v32, v191
	v_add_f32_e32 v33, v33, v186
	v_cvt_pk_bf16_f32 v86, v191, v186
	v_cvt_pk_bf16_f32 v87, v189, v201
	v_add_f32_e32 v34, v34, v189
	v_add_f32_e32 v35, v35, v201
	v_mfma_f32_32x32x16_bf16 v[16:31], v[100:103], v[84:87], v[16:31]
	v_mfma_f32_32x32x16_bf16 v[0:15], v[96:99], v[84:87], v[0:15]
	v_add_f32_e32 v32, v32, v204
	v_add_f32_e32 v33, v33, v205
	v_cvt_pk_bf16_f32 v80, v204, v205
	v_add_f32_e32 v34, v34, v212
	v_add_f32_e32 v35, v35, v213
	v_cvt_pk_bf16_f32 v81, v212, v213
	v_add_f32_e32 v32, v32, v219
	v_add_f32_e32 v33, v33, v220
	v_cvt_pk_bf16_f32 v82, v219, v220
	v_cvt_pk_bf16_f32 v83, v223, v224
	v_add_f32_e32 v34, v34, v223
	v_add_f32_e32 v35, v35, v224
	v_mfma_f32_32x32x16_bf16 v[16:31], v[108:111], v[80:83], v[16:31]
	v_mfma_f32_32x32x16_bf16 v[0:15], v[104:107], v[80:83], v[0:15]
	s_cbranch_vccnz .LBB0_1188
	v_pk_add_f32 v[70:71], v[70:71], v[172:173] op_sel_hi:[1,0] neg_lo:[0,1] neg_hi:[0,1]
	v_pk_add_f32 v[78:79], v[78:79], v[172:173] op_sel_hi:[1,0] neg_lo:[0,1] neg_hi:[0,1]
	v_pk_add_f32 v[64:65], v[64:65], v[172:173] op_sel_hi:[1,0] neg_lo:[0,1] neg_hi:[0,1]
	v_pk_add_f32 v[66:67], v[66:67], v[172:173] op_sel_hi:[1,0] neg_lo:[0,1] neg_hi:[0,1]
	v_pk_add_f32 v[68:69], v[68:69], v[172:173] op_sel_hi:[1,0] neg_lo:[0,1] neg_hi:[0,1]
	v_pk_add_f32 v[72:73], v[72:73], v[172:173] op_sel_hi:[1,0] neg_lo:[0,1] neg_hi:[0,1]
	v_pk_add_f32 v[74:75], v[74:75], v[172:173] op_sel_hi:[1,0] neg_lo:[0,1] neg_hi:[0,1]
	v_pk_add_f32 v[76:77], v[76:77], v[172:173] op_sel_hi:[1,0] neg_lo:[0,1] neg_hi:[0,1]
	v_pk_add_f32 v[62:63], v[62:63], v[172:173] op_sel_hi:[1,0] neg_lo:[0,1] neg_hi:[0,1]
	v_max_f32_e32 v82, v70, v71
	v_max_f32_e32 v85, v78, v79
	v_pk_add_f32 v[50:51], v[50:51], v[172:173] op_sel_hi:[1,0] neg_lo:[0,1] neg_hi:[0,1]
	v_pk_add_f32 v[54:55], v[54:55], v[172:173] op_sel_hi:[1,0] neg_lo:[0,1] neg_hi:[0,1]
	v_pk_add_f32 v[56:57], v[56:57], v[172:173] op_sel_hi:[1,0] neg_lo:[0,1] neg_hi:[0,1]
	v_pk_add_f32 v[58:59], v[58:59], v[172:173] op_sel_hi:[1,0] neg_lo:[0,1] neg_hi:[0,1]
	v_pk_add_f32 v[60:61], v[60:61], v[172:173] op_sel_hi:[1,0] neg_lo:[0,1] neg_hi:[0,1]
	v_max_f32_e32 v80, v64, v65
	v_max_f32_e32 v81, v66, v67
	v_max3_f32 v82, v68, v69, v82
	v_max_f32_e32 v83, v72, v73
	v_max_f32_e32 v84, v74, v75
	v_max3_f32 v85, v76, v77, v85
	v_max_f32_e32 v86, v62, v63
	v_pk_add_f32 v[48:49], v[48:49], v[172:173] op_sel_hi:[1,0] neg_lo:[0,1] neg_hi:[0,1]
	v_pk_add_f32 v[52:53], v[52:53], v[172:173] op_sel_hi:[1,0] neg_lo:[0,1] neg_hi:[0,1]
	v_max3_f32 v80, v80, v81, v82
	v_max3_f32 v81, v83, v84, v85
	v_max_f32_e32 v82, v50, v51
	v_max_f32_e32 v83, v54, v55
	v_max_f32_e32 v84, v56, v57
	v_max_f32_e32 v85, v58, v59
	v_max3_f32 v86, v60, v61, v86
	v_max3_f32 v82, v48, v49, v82
	v_max3_f32 v83, v52, v53, v83
	v_max3_f32 v84, v84, v85, v86
	v_max3_f32 v82, v82, v83, v84
	v_max3_f32 v80, v80, v81, v82
	ds_bpermute_b32 v81, v218, v80
	s_mov_b32 s14, 0x41000000
	s_waitcnt lgkmcnt(0)
	v_max_f32_e32 v81, v81, v81
	v_max_f32_e32 v80, v80, v81
	v_cmp_lt_f32_e32 vcc, s14, v80
	s_cbranch_vccz .LBB0_1188
	v_max_f32_e32 v80, v80, v80
	v_max_f32_e32 v81, 0, v80
	v_exp_f32_e64 v80, -v81
	v_sub_f32_e32 v79, v79, v81
	v_sub_f32_e32 v78, v78, v81
	v_sub_f32_e32 v77, v77, v81
	v_sub_f32_e32 v76, v76, v81
	v_sub_f32_e32 v75, v75, v81
	v_sub_f32_e32 v74, v74, v81
	v_sub_f32_e32 v73, v73, v81
	v_sub_f32_e32 v72, v72, v81
	v_sub_f32_e32 v71, v71, v81
	v_sub_f32_e32 v70, v70, v81
	v_sub_f32_e32 v69, v69, v81
	v_sub_f32_e32 v68, v68, v81
	v_sub_f32_e32 v67, v67, v81
	v_sub_f32_e32 v66, v66, v81
	v_sub_f32_e32 v65, v65, v81
	v_sub_f32_e32 v64, v64, v81
	v_sub_f32_e32 v63, v63, v81
	v_sub_f32_e32 v62, v62, v81
	v_sub_f32_e32 v61, v61, v81
	v_sub_f32_e32 v60, v60, v81
	v_sub_f32_e32 v59, v59, v81
	v_sub_f32_e32 v58, v58, v81
	v_sub_f32_e32 v57, v57, v81
	v_sub_f32_e32 v56, v56, v81
	v_sub_f32_e32 v55, v55, v81
	v_sub_f32_e32 v54, v54, v81
	v_sub_f32_e32 v53, v53, v81
	v_sub_f32_e32 v52, v52, v81
	v_sub_f32_e32 v51, v51, v81
	v_sub_f32_e32 v50, v50, v81
	v_sub_f32_e32 v49, v49, v81
	v_sub_f32_e32 v48, v48, v81
	v_pk_mul_f32 v[14:15], v[14:15], v[80:81] op_sel_hi:[1,0]
	v_pk_mul_f32 v[12:13], v[12:13], v[80:81] op_sel_hi:[1,0]
	v_pk_mul_f32 v[10:11], v[10:11], v[80:81] op_sel_hi:[1,0]
	v_pk_mul_f32 v[8:9], v[8:9], v[80:81] op_sel_hi:[1,0]
	v_pk_mul_f32 v[6:7], v[6:7], v[80:81] op_sel_hi:[1,0]
	v_pk_mul_f32 v[4:5], v[4:5], v[80:81] op_sel_hi:[1,0]
	v_pk_mul_f32 v[2:3], v[2:3], v[80:81] op_sel_hi:[1,0]
	v_pk_mul_f32 v[0:1], v[0:1], v[80:81] op_sel_hi:[1,0]
	v_pk_mul_f32 v[30:31], v[30:31], v[80:81] op_sel_hi:[1,0]
	v_pk_mul_f32 v[28:29], v[28:29], v[80:81] op_sel_hi:[1,0]
	v_pk_mul_f32 v[26:27], v[26:27], v[80:81] op_sel_hi:[1,0]
	v_pk_mul_f32 v[24:25], v[24:25], v[80:81] op_sel_hi:[1,0]
	v_pk_mul_f32 v[22:23], v[22:23], v[80:81] op_sel_hi:[1,0]
	v_pk_mul_f32 v[20:21], v[20:21], v[80:81] op_sel_hi:[1,0]
	v_pk_mul_f32 v[18:19], v[18:19], v[80:81] op_sel_hi:[1,0]
	v_pk_mul_f32 v[16:17], v[16:17], v[80:81] op_sel_hi:[1,0]
	v_pk_mul_f32 v[46:47], v[46:47], v[80:81] op_sel_hi:[1,0]
	v_pk_mul_f32 v[44:45], v[44:45], v[80:81] op_sel_hi:[1,0]
	v_pk_mul_f32 v[42:43], v[42:43], v[80:81] op_sel_hi:[1,0]
	v_pk_mul_f32 v[40:41], v[40:41], v[80:81] op_sel_hi:[1,0]
	v_pk_mul_f32 v[38:39], v[38:39], v[80:81] op_sel_hi:[1,0]
	v_pk_mul_f32 v[36:37], v[36:37], v[80:81] op_sel_hi:[1,0]
	v_pk_mul_f32 v[34:35], v[34:35], v[80:81] op_sel_hi:[1,0]
	v_pk_mul_f32 v[32:33], v[32:33], v[80:81] op_sel_hi:[1,0]
	v_add_f32_e32 v172, v172, v81
	s_branch .LBB0_1188
.LBB0_1209:
	s_mov_b64 s[8:9], 0xbd000
	v_lshl_add_u64 v[80:81], v[176:177], 0, s[8:9]
	s_mov_b32 m0, s57
	v_lshl_add_u64 v[82:83], v[80:81], 0, s[42:43]
	global_load_lds_dwordx4 v[82:83], off
	s_mov_b64 s[12:13], 0x1f00
	s_mov_b64 s[8:9], -1
	s_and_b64 vcc, exec, s[38:39]
	v_lshl_add_u64 v[82:83], v[178:179], 0, s[12:13]
	s_cbranch_vccz .LBB0_1211
	s_add_i32 m0, s18, s66
	s_mov_b64 s[8:9], 0
	global_load_lds_dwordx4 v[82:83], off
.LBB0_1211:
	s_mul_i32 s48, s61, 0x3000
	v_lshl_add_u64 v[84:85], v[142:143], 0, s[48:49]
	s_andn2_b64 vcc, exec, s[8:9]
	s_mov_b64 s[8:9], s[42:43]
	s_mov_b32 s12, s52
	s_cbranch_vccnz .LBB0_1213
	v_lshl_add_u64 v[80:81], v[80:81], 0, s[46:47]
	s_add_i32 m0, s56, 0x9000
	s_mov_b64 s[8:9], s[46:47]
	global_load_lds_dwordx4 v[80:81], off
	s_add_i32 m0, s18, s66
	v_lshl_add_u64 v[80:81], v[84:85], 0, s[42:43]
	global_load_lds_dwordx4 v[82:83], off
	s_mov_b32 m0, s16
	s_mov_b32 s12, s56
	global_load_lds_dwordx4 v[80:81], off
.LBB0_1213:
	s_mov_b32 m0, s12
	v_lshl_add_u64 v[80:81], v[84:85], 0, s[8:9]
	s_mov_b64 s[8:9], 0x1f80
	global_load_lds_dwordx4 v[80:81], off
	v_lshl_add_u64 v[80:81], v[178:179], 0, s[8:9]
	s_add_i32 m0, s17, s66
	v_exp_f32_e32 v150, v64
	global_load_lds_dwordx4 v[80:81], off
	ds_read_b128 v[80:83], v199 offset:12288
	ds_read_b128 v[84:87], v199 offset:18432
	ds_read_b128 v[154:157], v200 offset:12288
	ds_read_b128 v[176:179], v200 offset:18432
	ds_read_b128 v[180:183], v199 offset:12352
	ds_read_b128 v[184:187], v199 offset:18496
	ds_read_b128 v[188:191], v200 offset:12352
	ds_read_b128 v[202:205], v200 offset:18496
	ds_read_b128 v[212:215], v199 offset:12416
	ds_read_b128 v[220:223], v199 offset:18560
	ds_read_b128 v[224:227], v200 offset:12416
	ds_read_b128 v[228:231], v200 offset:18560
	s_waitcnt lgkmcnt(0)
	v_mfma_f32_32x32x16_bf16 v[96:111], v[80:83], v[136:139], 0
	v_exp_f32_e32 v151, v65
	v_exp_f32_e32 v152, v48
	v_exp_f32_e32 v153, v49
	v_exp_f32_e32 v167, v50
	v_exp_f32_e32 v169, v51
	v_exp_f32_e32 v201, v77
	v_exp_f32_e32 v208, v62
	v_mfma_f32_32x32x16_bf16 v[80:95], v[84:87], v[136:139], 0
	v_exp_f32_e32 v209, v63
	v_mfma_f32_32x32x16_bf16 v[96:111], v[154:157], v[132:135], v[96:111]
	v_exp_f32_e32 v155, v66
	v_exp_f32_e32 v156, v67
	v_exp_f32_e32 v157, v68
	v_mfma_f32_32x32x16_bf16 v[96:111], v[180:183], v[128:131], v[96:111]
	v_exp_f32_e32 v180, v69
	v_exp_f32_e32 v181, v52
	v_exp_f32_e32 v182, v55
	v_exp_f32_e32 v183, v72
	v_mfma_f32_32x32x16_bf16 v[96:111], v[188:191], v[124:127], v[96:111]
	v_exp_f32_e32 v188, v73
	v_exp_f32_e32 v189, v58
	v_exp_f32_e32 v190, v59
	v_exp_f32_e32 v191, v76
	v_mfma_f32_32x32x16_bf16 v[96:111], v[212:215], v[120:123], v[96:111]
	v_mfma_f32_32x32x16_bf16 v[96:111], v[224:227], v[116:119], v[96:111]
	v_mfma_f32_32x32x16_bf16 v[80:95], v[176:179], v[132:135], v[80:95]
	v_exp_f32_e32 v176, v53
	v_exp_f32_e32 v177, v70
	v_exp_f32_e32 v178, v71
	v_exp_f32_e32 v179, v54
	v_mfma_f32_32x32x16_bf16 v[80:95], v[184:187], v[128:131], v[80:95]
	v_exp_f32_e32 v184, v56
	v_exp_f32_e32 v185, v57
	v_exp_f32_e32 v186, v74
	v_exp_f32_e32 v187, v75
	v_mfma_f32_32x32x16_bf16 v[80:95], v[202:205], v[124:127], v[80:95]
	v_exp_f32_e32 v202, v60
	v_exp_f32_e32 v203, v61
	v_exp_f32_e32 v204, v78
	v_exp_f32_e32 v205, v79
	v_mfma_f32_32x32x16_bf16 v[80:95], v[220:223], v[120:123], v[80:95]
	ds_read_b128 v[48:51], v173 offset:49152
	ds_read_b128 v[52:55], v173 offset:53248
	ds_read_b128 v[56:59], v197 offset:49152
	ds_read_b128 v[60:63], v197 offset:53248
	ds_read_b128 v[64:67], v193 offset:49152
	ds_read_b128 v[68:71], v193 offset:53248
	ds_read_b128 v[72:75], v195 offset:49152
	ds_read_b128 v[76:79], v195 offset:53248
	v_add_f32_e32 v32, v32, v150
	v_add_f32_e32 v33, v33, v151
	v_cvt_pk_bf16_f32 v154, v150, v151
	v_add_f32_e32 v34, v34, v155
	v_add_f32_e32 v35, v35, v156
	v_cvt_pk_bf16_f32 v155, v155, v156
	v_add_f32_e32 v32, v32, v157
	v_add_f32_e32 v33, v33, v180
	v_cvt_pk_bf16_f32 v156, v157, v180
	v_add_f32_e32 v34, v34, v177
	v_add_f32_e32 v35, v35, v178
	v_cvt_pk_bf16_f32 v157, v177, v178
	v_mfma_f32_32x32x16_bf16 v[80:95], v[228:231], v[116:119], v[80:95]
	s_and_b64 vcc, exec, s[6:7]
	s_waitcnt lgkmcnt(0)
	v_mfma_f32_32x32x16_bf16 v[16:31], v[52:55], v[154:157], v[16:31]
	v_mfma_f32_32x32x16_bf16 v[0:15], v[48:51], v[154:157], v[0:15]
	v_add_f32_e32 v32, v32, v183
	v_add_f32_e32 v33, v33, v188
	v_cvt_pk_bf16_f32 v48, v183, v188
	v_add_f32_e32 v34, v34, v186
	v_add_f32_e32 v35, v35, v187
	v_cvt_pk_bf16_f32 v49, v186, v187
	v_add_f32_e32 v32, v32, v191
	v_add_f32_e32 v33, v33, v201
	v_cvt_pk_bf16_f32 v50, v191, v201
	v_cvt_pk_bf16_f32 v51, v204, v205
	v_add_f32_e32 v34, v34, v204
	v_add_f32_e32 v35, v35, v205
	v_mfma_f32_32x32x16_bf16 v[16:31], v[60:63], v[48:51], v[16:31]
	v_mfma_f32_32x32x16_bf16 v[0:15], v[56:59], v[48:51], v[0:15]
	v_add_f32_e32 v32, v32, v152
	v_add_f32_e32 v33, v33, v153
	v_cvt_pk_bf16_f32 v52, v152, v153
	v_add_f32_e32 v34, v34, v167
	v_add_f32_e32 v35, v35, v169
	v_cvt_pk_bf16_f32 v53, v167, v169
	v_add_f32_e32 v32, v32, v181
	v_add_f32_e32 v33, v33, v176
	v_cvt_pk_bf16_f32 v54, v181, v176
	v_cvt_pk_bf16_f32 v55, v179, v182
	v_add_f32_e32 v34, v34, v179
	v_add_f32_e32 v35, v35, v182
	v_mfma_f32_32x32x16_bf16 v[16:31], v[68:71], v[52:55], v[16:31]
	v_mfma_f32_32x32x16_bf16 v[0:15], v[64:67], v[52:55], v[0:15]
	v_add_f32_e32 v32, v32, v184
	v_add_f32_e32 v33, v33, v185
	v_cvt_pk_bf16_f32 v48, v184, v185
	v_add_f32_e32 v34, v34, v189
	v_add_f32_e32 v35, v35, v190
	v_cvt_pk_bf16_f32 v49, v189, v190
	v_add_f32_e32 v32, v32, v202
	v_add_f32_e32 v33, v33, v203
	v_cvt_pk_bf16_f32 v50, v202, v203
	v_cvt_pk_bf16_f32 v51, v208, v209
	v_add_f32_e32 v34, v34, v208
	v_add_f32_e32 v35, v35, v209
	v_mfma_f32_32x32x16_bf16 v[16:31], v[76:79], v[48:51], v[16:31]
	v_mfma_f32_32x32x16_bf16 v[0:15], v[72:75], v[48:51], v[0:15]
	s_cbranch_vccnz .LBB0_1216
	v_pk_add_f32 v[102:103], v[102:103], v[172:173] op_sel_hi:[1,0] neg_lo:[0,1] neg_hi:[0,1]
	v_pk_add_f32 v[110:111], v[110:111], v[172:173] op_sel_hi:[1,0] neg_lo:[0,1] neg_hi:[0,1]
	v_pk_add_f32 v[96:97], v[96:97], v[172:173] op_sel_hi:[1,0] neg_lo:[0,1] neg_hi:[0,1]
	v_pk_add_f32 v[98:99], v[98:99], v[172:173] op_sel_hi:[1,0] neg_lo:[0,1] neg_hi:[0,1]
	v_pk_add_f32 v[100:101], v[100:101], v[172:173] op_sel_hi:[1,0] neg_lo:[0,1] neg_hi:[0,1]
	v_pk_add_f32 v[104:105], v[104:105], v[172:173] op_sel_hi:[1,0] neg_lo:[0,1] neg_hi:[0,1]
	v_pk_add_f32 v[106:107], v[106:107], v[172:173] op_sel_hi:[1,0] neg_lo:[0,1] neg_hi:[0,1]
	v_pk_add_f32 v[108:109], v[108:109], v[172:173] op_sel_hi:[1,0] neg_lo:[0,1] neg_hi:[0,1]
	v_pk_add_f32 v[94:95], v[94:95], v[172:173] op_sel_hi:[1,0] neg_lo:[0,1] neg_hi:[0,1]
	v_max_f32_e32 v50, v102, v103
	v_max_f32_e32 v53, v110, v111
	v_pk_add_f32 v[82:83], v[82:83], v[172:173] op_sel_hi:[1,0] neg_lo:[0,1] neg_hi:[0,1]
	v_pk_add_f32 v[86:87], v[86:87], v[172:173] op_sel_hi:[1,0] neg_lo:[0,1] neg_hi:[0,1]
	v_pk_add_f32 v[88:89], v[88:89], v[172:173] op_sel_hi:[1,0] neg_lo:[0,1] neg_hi:[0,1]
	v_pk_add_f32 v[90:91], v[90:91], v[172:173] op_sel_hi:[1,0] neg_lo:[0,1] neg_hi:[0,1]
	v_pk_add_f32 v[92:93], v[92:93], v[172:173] op_sel_hi:[1,0] neg_lo:[0,1] neg_hi:[0,1]
	v_max_f32_e32 v48, v96, v97
	v_max_f32_e32 v49, v98, v99
	v_max3_f32 v50, v100, v101, v50
	v_max_f32_e32 v51, v104, v105
	v_max_f32_e32 v52, v106, v107
	v_max3_f32 v53, v108, v109, v53
	v_max_f32_e32 v54, v94, v95
	v_pk_add_f32 v[80:81], v[80:81], v[172:173] op_sel_hi:[1,0] neg_lo:[0,1] neg_hi:[0,1]
	v_pk_add_f32 v[84:85], v[84:85], v[172:173] op_sel_hi:[1,0] neg_lo:[0,1] neg_hi:[0,1]
	v_max3_f32 v48, v48, v49, v50
	v_max3_f32 v49, v51, v52, v53
	v_max_f32_e32 v50, v82, v83
	v_max_f32_e32 v51, v86, v87
	v_max_f32_e32 v52, v88, v89
	v_max_f32_e32 v53, v90, v91
	v_max3_f32 v54, v92, v93, v54
	v_max3_f32 v50, v80, v81, v50
	v_max3_f32 v51, v84, v85, v51
	v_max3_f32 v52, v52, v53, v54
	v_max3_f32 v50, v50, v51, v52
	v_max3_f32 v48, v48, v49, v50
	ds_bpermute_b32 v49, v218, v48
	s_mov_b32 s8, 0x41000000
	s_waitcnt lgkmcnt(0)
	v_max_f32_e32 v49, v49, v49
	v_max_f32_e32 v48, v48, v49
	v_cmp_lt_f32_e32 vcc, s8, v48
	s_cbranch_vccz .LBB0_1216
	v_max_f32_e32 v48, v48, v48
	v_max_f32_e32 v49, 0, v48
	v_exp_f32_e64 v48, -v49
	v_sub_f32_e32 v96, v96, v49
	v_sub_f32_e32 v97, v97, v49
	v_sub_f32_e32 v98, v98, v49
	v_sub_f32_e32 v99, v99, v49
	v_sub_f32_e32 v100, v100, v49
	v_sub_f32_e32 v101, v101, v49
	v_sub_f32_e32 v102, v102, v49
	v_sub_f32_e32 v103, v103, v49
	v_sub_f32_e32 v104, v104, v49
	v_sub_f32_e32 v105, v105, v49
	v_sub_f32_e32 v106, v106, v49
	v_sub_f32_e32 v107, v107, v49
	v_sub_f32_e32 v108, v108, v49
	v_sub_f32_e32 v109, v109, v49
	v_sub_f32_e32 v110, v110, v49
	v_sub_f32_e32 v111, v111, v49
	v_sub_f32_e32 v80, v80, v49
	v_sub_f32_e32 v81, v81, v49
	v_sub_f32_e32 v82, v82, v49
	v_sub_f32_e32 v83, v83, v49
	v_sub_f32_e32 v84, v84, v49
	v_sub_f32_e32 v85, v85, v49
	v_sub_f32_e32 v86, v86, v49
	v_sub_f32_e32 v87, v87, v49
	v_sub_f32_e32 v88, v88, v49
	v_sub_f32_e32 v89, v89, v49
	v_sub_f32_e32 v90, v90, v49
	v_sub_f32_e32 v91, v91, v49
	v_sub_f32_e32 v92, v92, v49
	v_sub_f32_e32 v93, v93, v49
	v_sub_f32_e32 v94, v94, v49
	v_sub_f32_e32 v95, v95, v49
	v_pk_mul_f32 v[14:15], v[14:15], v[48:49] op_sel_hi:[1,0]
	v_pk_mul_f32 v[12:13], v[12:13], v[48:49] op_sel_hi:[1,0]
	v_pk_mul_f32 v[10:11], v[10:11], v[48:49] op_sel_hi:[1,0]
	v_pk_mul_f32 v[8:9], v[8:9], v[48:49] op_sel_hi:[1,0]
	v_pk_mul_f32 v[6:7], v[6:7], v[48:49] op_sel_hi:[1,0]
	v_pk_mul_f32 v[4:5], v[4:5], v[48:49] op_sel_hi:[1,0]
	v_pk_mul_f32 v[2:3], v[2:3], v[48:49] op_sel_hi:[1,0]
	v_pk_mul_f32 v[0:1], v[0:1], v[48:49] op_sel_hi:[1,0]
	v_pk_mul_f32 v[30:31], v[30:31], v[48:49] op_sel_hi:[1,0]
	v_pk_mul_f32 v[28:29], v[28:29], v[48:49] op_sel_hi:[1,0]
	v_pk_mul_f32 v[26:27], v[26:27], v[48:49] op_sel_hi:[1,0]
	v_pk_mul_f32 v[24:25], v[24:25], v[48:49] op_sel_hi:[1,0]
	v_pk_mul_f32 v[22:23], v[22:23], v[48:49] op_sel_hi:[1,0]
	v_pk_mul_f32 v[20:21], v[20:21], v[48:49] op_sel_hi:[1,0]
	v_pk_mul_f32 v[18:19], v[18:19], v[48:49] op_sel_hi:[1,0]
	v_pk_mul_f32 v[16:17], v[16:17], v[48:49] op_sel_hi:[1,0]
	v_pk_mul_f32 v[46:47], v[46:47], v[48:49] op_sel_hi:[1,0]
	v_pk_mul_f32 v[44:45], v[44:45], v[48:49] op_sel_hi:[1,0]
	v_pk_mul_f32 v[42:43], v[42:43], v[48:49] op_sel_hi:[1,0]
	v_pk_mul_f32 v[40:41], v[40:41], v[48:49] op_sel_hi:[1,0]
	v_pk_mul_f32 v[38:39], v[38:39], v[48:49] op_sel_hi:[1,0]
	v_pk_mul_f32 v[36:37], v[36:37], v[48:49] op_sel_hi:[1,0]
	v_pk_mul_f32 v[34:35], v[34:35], v[48:49] op_sel_hi:[1,0]
	v_pk_mul_f32 v[32:33], v[32:33], v[48:49] op_sel_hi:[1,0]
	v_add_f32_e32 v172, v172, v49
.LBB0_1216:
	ds_read_b128 v[48:51], v199 offset:24576
	ds_read_b128 v[52:55], v199 offset:30720
	ds_read_b128 v[154:157], v200 offset:24576
	ds_read_b128 v[176:179], v200 offset:30720
	ds_read_b128 v[180:183], v199 offset:24640
	ds_read_b128 v[184:187], v199 offset:30784
	ds_read_b128 v[188:191], v200 offset:24640
	ds_read_b128 v[202:205], v200 offset:30784
	ds_read_b128 v[212:215], v199 offset:24704
	ds_read_b128 v[220:223], v199 offset:30848
	ds_read_b128 v[224:227], v200 offset:24704
	ds_read_b128 v[228:231], v200 offset:30848
	s_waitcnt lgkmcnt(0)
	v_mfma_f32_32x32x16_bf16 v[64:79], v[48:51], v[136:139], 0
	v_exp_f32_e32 v150, v96
	v_exp_f32_e32 v151, v97
	v_exp_f32_e32 v152, v80
	v_exp_f32_e32 v153, v81
	v_exp_f32_e32 v167, v82
	v_exp_f32_e32 v169, v83
	v_exp_f32_e32 v201, v109
	v_mfma_f32_32x32x16_bf16 v[48:63], v[52:55], v[136:139], 0
	v_exp_f32_e32 v208, v94
	v_exp_f32_e32 v209, v95
	v_mfma_f32_32x32x16_bf16 v[64:79], v[154:157], v[132:135], v[64:79]
	v_exp_f32_e32 v155, v98
	v_exp_f32_e32 v156, v99
	v_exp_f32_e32 v157, v100
	v_mfma_f32_32x32x16_bf16 v[64:79], v[180:183], v[128:131], v[64:79]
	v_exp_f32_e32 v180, v101
	v_exp_f32_e32 v181, v84
	v_exp_f32_e32 v182, v87
	v_exp_f32_e32 v183, v104
	v_mfma_f32_32x32x16_bf16 v[64:79], v[188:191], v[124:127], v[64:79]
	v_exp_f32_e32 v188, v105
	v_exp_f32_e32 v189, v90
	v_exp_f32_e32 v190, v91
	v_exp_f32_e32 v191, v108
	v_mfma_f32_32x32x16_bf16 v[64:79], v[212:215], v[120:123], v[64:79]
	v_mfma_f32_32x32x16_bf16 v[64:79], v[224:227], v[116:119], v[64:79]
	v_mfma_f32_32x32x16_bf16 v[48:63], v[176:179], v[132:135], v[48:63]
	v_exp_f32_e32 v176, v85
	v_exp_f32_e32 v177, v102
	v_exp_f32_e32 v178, v103
	v_exp_f32_e32 v179, v86
	v_mfma_f32_32x32x16_bf16 v[48:63], v[184:187], v[128:131], v[48:63]
	v_exp_f32_e32 v184, v88
	v_exp_f32_e32 v185, v89
	v_exp_f32_e32 v186, v106
	v_exp_f32_e32 v187, v107
	v_mfma_f32_32x32x16_bf16 v[48:63], v[202:205], v[124:127], v[48:63]
	v_exp_f32_e32 v202, v92
	v_exp_f32_e32 v203, v93
	v_exp_f32_e32 v204, v110
	v_exp_f32_e32 v205, v111
	v_mfma_f32_32x32x16_bf16 v[48:63], v[220:223], v[120:123], v[48:63]
	ds_read_b128 v[80:83], v173 offset:57344
	ds_read_b128 v[84:87], v173 offset:61440
	ds_read_b128 v[88:91], v197 offset:57344
	ds_read_b128 v[92:95], v197 offset:61440
	ds_read_b128 v[96:99], v193 offset:57344
	ds_read_b128 v[100:103], v193 offset:61440
	ds_read_b128 v[104:107], v195 offset:57344
	ds_read_b128 v[108:111], v195 offset:61440
	v_add_f32_e32 v32, v32, v150
	v_add_f32_e32 v33, v33, v151
	v_cvt_pk_bf16_f32 v154, v150, v151
	v_add_f32_e32 v34, v34, v155
	v_add_f32_e32 v35, v35, v156
	v_cvt_pk_bf16_f32 v155, v155, v156
	v_add_f32_e32 v32, v32, v157
	v_add_f32_e32 v33, v33, v180
	v_cvt_pk_bf16_f32 v156, v157, v180
	v_add_f32_e32 v34, v34, v177
	v_add_f32_e32 v35, v35, v178
	v_cvt_pk_bf16_f32 v157, v177, v178
	v_mfma_f32_32x32x16_bf16 v[48:63], v[228:231], v[116:119], v[48:63]
	s_cmp_eq_u32 s64, 0
	s_cbranch_scc1 .Lmla_late_skip2
	s_waitcnt vmcnt(0)
	s_barrier
.Lmla_late_skip2:
	s_and_b64 vcc, exec, s[6:7]
	s_waitcnt lgkmcnt(0)
	v_mfma_f32_32x32x16_bf16 v[16:31], v[84:87], v[154:157], v[16:31]
	v_mfma_f32_32x32x16_bf16 v[0:15], v[80:83], v[154:157], v[0:15]
	v_add_f32_e32 v32, v32, v183
	v_add_f32_e32 v33, v33, v188
	v_cvt_pk_bf16_f32 v80, v183, v188
	v_add_f32_e32 v34, v34, v186
	v_add_f32_e32 v35, v35, v187
	v_cvt_pk_bf16_f32 v81, v186, v187
	v_add_f32_e32 v32, v32, v191
	v_add_f32_e32 v33, v33, v201
	v_cvt_pk_bf16_f32 v82, v191, v201
	v_cvt_pk_bf16_f32 v83, v204, v205
	v_add_f32_e32 v34, v34, v204
	v_add_f32_e32 v35, v35, v205
	v_mfma_f32_32x32x16_bf16 v[16:31], v[92:95], v[80:83], v[16:31]
	v_mfma_f32_32x32x16_bf16 v[0:15], v[88:91], v[80:83], v[0:15]
	v_add_f32_e32 v32, v32, v152
	v_add_f32_e32 v33, v33, v153
	v_cvt_pk_bf16_f32 v84, v152, v153
	v_add_f32_e32 v34, v34, v167
	v_add_f32_e32 v35, v35, v169
	v_cvt_pk_bf16_f32 v85, v167, v169
	v_add_f32_e32 v32, v32, v181
	v_add_f32_e32 v33, v33, v176
	v_cvt_pk_bf16_f32 v86, v181, v176
	v_cvt_pk_bf16_f32 v87, v179, v182
	v_add_f32_e32 v34, v34, v179
	v_add_f32_e32 v35, v35, v182
	v_mfma_f32_32x32x16_bf16 v[16:31], v[100:103], v[84:87], v[16:31]
	v_mfma_f32_32x32x16_bf16 v[0:15], v[96:99], v[84:87], v[0:15]
	v_add_f32_e32 v32, v32, v184
	v_add_f32_e32 v33, v33, v185
	v_cvt_pk_bf16_f32 v80, v184, v185
	v_add_f32_e32 v34, v34, v189
	v_add_f32_e32 v35, v35, v190
	v_cvt_pk_bf16_f32 v81, v189, v190
	v_add_f32_e32 v32, v32, v202
	v_add_f32_e32 v33, v33, v203
	v_cvt_pk_bf16_f32 v82, v202, v203
	v_cvt_pk_bf16_f32 v83, v208, v209
	v_add_f32_e32 v34, v34, v208
	v_add_f32_e32 v35, v35, v209
	v_mfma_f32_32x32x16_bf16 v[16:31], v[108:111], v[80:83], v[16:31]
	v_mfma_f32_32x32x16_bf16 v[0:15], v[104:107], v[80:83], v[0:15]
	s_cbranch_vccnz .LBB0_1219
	v_pk_add_f32 v[70:71], v[70:71], v[172:173] op_sel_hi:[1,0] neg_lo:[0,1] neg_hi:[0,1]
	v_pk_add_f32 v[78:79], v[78:79], v[172:173] op_sel_hi:[1,0] neg_lo:[0,1] neg_hi:[0,1]
	v_pk_add_f32 v[64:65], v[64:65], v[172:173] op_sel_hi:[1,0] neg_lo:[0,1] neg_hi:[0,1]
	v_pk_add_f32 v[66:67], v[66:67], v[172:173] op_sel_hi:[1,0] neg_lo:[0,1] neg_hi:[0,1]
	v_pk_add_f32 v[68:69], v[68:69], v[172:173] op_sel_hi:[1,0] neg_lo:[0,1] neg_hi:[0,1]
	v_pk_add_f32 v[72:73], v[72:73], v[172:173] op_sel_hi:[1,0] neg_lo:[0,1] neg_hi:[0,1]
	v_pk_add_f32 v[74:75], v[74:75], v[172:173] op_sel_hi:[1,0] neg_lo:[0,1] neg_hi:[0,1]
	v_pk_add_f32 v[76:77], v[76:77], v[172:173] op_sel_hi:[1,0] neg_lo:[0,1] neg_hi:[0,1]
	v_pk_add_f32 v[62:63], v[62:63], v[172:173] op_sel_hi:[1,0] neg_lo:[0,1] neg_hi:[0,1]
	v_max_f32_e32 v82, v70, v71
	v_max_f32_e32 v85, v78, v79
	v_pk_add_f32 v[50:51], v[50:51], v[172:173] op_sel_hi:[1,0] neg_lo:[0,1] neg_hi:[0,1]
	v_pk_add_f32 v[54:55], v[54:55], v[172:173] op_sel_hi:[1,0] neg_lo:[0,1] neg_hi:[0,1]
	v_pk_add_f32 v[56:57], v[56:57], v[172:173] op_sel_hi:[1,0] neg_lo:[0,1] neg_hi:[0,1]
	v_pk_add_f32 v[58:59], v[58:59], v[172:173] op_sel_hi:[1,0] neg_lo:[0,1] neg_hi:[0,1]
	v_pk_add_f32 v[60:61], v[60:61], v[172:173] op_sel_hi:[1,0] neg_lo:[0,1] neg_hi:[0,1]
	v_max_f32_e32 v80, v64, v65
	v_max_f32_e32 v81, v66, v67
	v_max3_f32 v82, v68, v69, v82
	v_max_f32_e32 v83, v72, v73
	v_max_f32_e32 v84, v74, v75
	v_max3_f32 v85, v76, v77, v85
	v_max_f32_e32 v86, v62, v63
	v_pk_add_f32 v[48:49], v[48:49], v[172:173] op_sel_hi:[1,0] neg_lo:[0,1] neg_hi:[0,1]
	v_pk_add_f32 v[52:53], v[52:53], v[172:173] op_sel_hi:[1,0] neg_lo:[0,1] neg_hi:[0,1]
	v_max3_f32 v80, v80, v81, v82
	v_max3_f32 v81, v83, v84, v85
	v_max_f32_e32 v82, v50, v51
	v_max_f32_e32 v83, v54, v55
	v_max_f32_e32 v84, v56, v57
	v_max_f32_e32 v85, v58, v59
	v_max3_f32 v86, v60, v61, v86
	v_max3_f32 v82, v48, v49, v82
	v_max3_f32 v83, v52, v53, v83
	v_max3_f32 v84, v84, v85, v86
	v_max3_f32 v82, v82, v83, v84
	v_max3_f32 v80, v80, v81, v82
	ds_bpermute_b32 v81, v218, v80
	s_mov_b32 s8, 0x41000000
	s_waitcnt lgkmcnt(0)
	v_max_f32_e32 v81, v81, v81
	v_max_f32_e32 v80, v80, v81
	v_cmp_lt_f32_e32 vcc, s8, v80
	s_cbranch_vccz .LBB0_1219
	v_max_f32_e32 v80, v80, v80
	v_max_f32_e32 v81, 0, v80
	v_exp_f32_e64 v80, -v81
	v_sub_f32_e32 v64, v64, v81
	v_sub_f32_e32 v65, v65, v81
	v_sub_f32_e32 v66, v66, v81
	v_sub_f32_e32 v67, v67, v81
	v_sub_f32_e32 v68, v68, v81
	v_sub_f32_e32 v69, v69, v81
	v_sub_f32_e32 v70, v70, v81
	v_sub_f32_e32 v71, v71, v81
	v_sub_f32_e32 v72, v72, v81
	v_sub_f32_e32 v73, v73, v81
	v_sub_f32_e32 v74, v74, v81
	v_sub_f32_e32 v75, v75, v81
	v_sub_f32_e32 v76, v76, v81
	v_sub_f32_e32 v77, v77, v81
	v_sub_f32_e32 v78, v78, v81
	v_sub_f32_e32 v79, v79, v81
	v_sub_f32_e32 v48, v48, v81
	v_sub_f32_e32 v49, v49, v81
	v_sub_f32_e32 v50, v50, v81
	v_sub_f32_e32 v51, v51, v81
	v_sub_f32_e32 v52, v52, v81
	v_sub_f32_e32 v53, v53, v81
	v_sub_f32_e32 v54, v54, v81
	v_sub_f32_e32 v55, v55, v81
	v_sub_f32_e32 v56, v56, v81
	v_sub_f32_e32 v57, v57, v81
	v_sub_f32_e32 v58, v58, v81
	v_sub_f32_e32 v59, v59, v81
	v_sub_f32_e32 v60, v60, v81
	v_sub_f32_e32 v61, v61, v81
	v_sub_f32_e32 v62, v62, v81
	v_sub_f32_e32 v63, v63, v81
	v_pk_mul_f32 v[14:15], v[14:15], v[80:81] op_sel_hi:[1,0]
	v_pk_mul_f32 v[12:13], v[12:13], v[80:81] op_sel_hi:[1,0]
	v_pk_mul_f32 v[10:11], v[10:11], v[80:81] op_sel_hi:[1,0]
	v_pk_mul_f32 v[8:9], v[8:9], v[80:81] op_sel_hi:[1,0]
	v_pk_mul_f32 v[6:7], v[6:7], v[80:81] op_sel_hi:[1,0]
	v_pk_mul_f32 v[4:5], v[4:5], v[80:81] op_sel_hi:[1,0]
	v_pk_mul_f32 v[2:3], v[2:3], v[80:81] op_sel_hi:[1,0]
	v_pk_mul_f32 v[0:1], v[0:1], v[80:81] op_sel_hi:[1,0]
	v_pk_mul_f32 v[30:31], v[30:31], v[80:81] op_sel_hi:[1,0]
	v_pk_mul_f32 v[28:29], v[28:29], v[80:81] op_sel_hi:[1,0]
	v_pk_mul_f32 v[26:27], v[26:27], v[80:81] op_sel_hi:[1,0]
	v_pk_mul_f32 v[24:25], v[24:25], v[80:81] op_sel_hi:[1,0]
	v_pk_mul_f32 v[22:23], v[22:23], v[80:81] op_sel_hi:[1,0]
	v_pk_mul_f32 v[20:21], v[20:21], v[80:81] op_sel_hi:[1,0]
	v_pk_mul_f32 v[18:19], v[18:19], v[80:81] op_sel_hi:[1,0]
	v_pk_mul_f32 v[16:17], v[16:17], v[80:81] op_sel_hi:[1,0]
	v_pk_mul_f32 v[46:47], v[46:47], v[80:81] op_sel_hi:[1,0]
	v_pk_mul_f32 v[44:45], v[44:45], v[80:81] op_sel_hi:[1,0]
	v_pk_mul_f32 v[42:43], v[42:43], v[80:81] op_sel_hi:[1,0]
	v_pk_mul_f32 v[40:41], v[40:41], v[80:81] op_sel_hi:[1,0]
	v_pk_mul_f32 v[38:39], v[38:39], v[80:81] op_sel_hi:[1,0]
	v_pk_mul_f32 v[36:37], v[36:37], v[80:81] op_sel_hi:[1,0]
	v_pk_mul_f32 v[34:35], v[34:35], v[80:81] op_sel_hi:[1,0]
	v_pk_mul_f32 v[32:33], v[32:33], v[80:81] op_sel_hi:[1,0]
	v_add_f32_e32 v172, v172, v81
.LBB0_1219:
	v_lshlrev_b64 v[80:81], 7, v[174:175]
	v_lshl_add_u64 v[80:81], v[144:145], 0, v[80:81]
	s_cmp_lg_u32 s64, 0
	s_cbranch_scc1 .Lmla_early_skip2
	s_waitcnt vmcnt(0)
	s_waitcnt vmcnt(0)
	s_barrier
.Lmla_early_skip2:
	s_sub_i32 m0, s60, s66
	s_add_i32 m0, m0, 0x8000
	v_exp_f32_e32 v150, v64
	global_load_lds_dwordx4 v[80:81], off
	ds_read_b128 v[80:83], v199 offset:36864
	ds_read_b128 v[84:87], v199 offset:43008
	ds_read_b128 v[154:157], v200 offset:36864
	ds_read_b128 v[174:177], v200 offset:43008
	ds_read_b128 v[178:181], v199 offset:36928
	ds_read_b128 v[182:185], v199 offset:43072
	ds_read_b128 v[186:189], v200 offset:36928
	ds_read_b128 v[202:205], v200 offset:43072
	ds_read_b128 v[212:215], v199 offset:36992
	ds_read_b128 v[220:223], v199 offset:43136
	ds_read_b128 v[224:227], v200 offset:36992
	ds_read_b128 v[228:231], v200 offset:43136
	s_waitcnt lgkmcnt(0)
	v_mfma_f32_32x32x16_bf16 v[96:111], v[80:83], v[136:139], 0
	v_exp_f32_e32 v151, v65
	v_exp_f32_e32 v152, v48
	v_exp_f32_e32 v153, v49
	v_exp_f32_e32 v167, v50
	v_exp_f32_e32 v169, v51
	v_exp_f32_e32 v190, v77
	v_exp_f32_e32 v191, v60
	v_mfma_f32_32x32x16_bf16 v[80:95], v[84:87], v[136:139], 0
	v_exp_f32_e32 v201, v61
	v_mfma_f32_32x32x16_bf16 v[96:111], v[154:157], v[132:135], v[96:111]
	v_exp_f32_e32 v155, v66
	v_exp_f32_e32 v156, v67
	v_exp_f32_e32 v157, v68
	v_mfma_f32_32x32x16_bf16 v[96:111], v[178:181], v[128:131], v[96:111]
	v_exp_f32_e32 v178, v69
	v_exp_f32_e32 v179, v52
	v_exp_f32_e32 v180, v55
	v_exp_f32_e32 v181, v72
	v_mfma_f32_32x32x16_bf16 v[96:111], v[186:189], v[124:127], v[96:111]
	v_exp_f32_e32 v186, v73
	v_exp_f32_e32 v187, v58
	v_exp_f32_e32 v188, v59
	v_exp_f32_e32 v189, v76
	v_mfma_f32_32x32x16_bf16 v[96:111], v[212:215], v[120:123], v[96:111]
	v_mfma_f32_32x32x16_bf16 v[96:111], v[224:227], v[116:119], v[96:111]
	v_mfma_f32_32x32x16_bf16 v[80:95], v[174:177], v[132:135], v[80:95]
	v_exp_f32_e32 v174, v53
	v_exp_f32_e32 v175, v70
	v_exp_f32_e32 v176, v71
	v_exp_f32_e32 v177, v54
	v_mfma_f32_32x32x16_bf16 v[80:95], v[182:185], v[128:131], v[80:95]
	v_exp_f32_e32 v182, v56
	v_exp_f32_e32 v183, v57
	v_exp_f32_e32 v184, v74
	v_exp_f32_e32 v185, v75
	v_mfma_f32_32x32x16_bf16 v[80:95], v[202:205], v[124:127], v[80:95]
	v_exp_f32_e32 v202, v78
	v_exp_f32_e32 v203, v79
	v_exp_f32_e32 v204, v62
	v_exp_f32_e32 v205, v63
	v_mfma_f32_32x32x16_bf16 v[80:95], v[220:223], v[120:123], v[80:95]
	ds_read_b128 v[48:51], v192 offset:16384
	ds_read_b128 v[52:55], v192 offset:20480
	ds_read_b128 v[56:59], v198 offset:16384
	ds_read_b128 v[60:63], v198 offset:20480
	ds_read_b128 v[64:67], v194 offset:16384
	ds_read_b128 v[68:71], v194 offset:20480
	ds_read_b128 v[72:75], v196 offset:16384
	ds_read_b128 v[76:79], v196 offset:20480
	v_add_f32_e32 v32, v32, v150
	v_add_f32_e32 v33, v33, v151
	v_cvt_pk_bf16_f32 v154, v150, v151
	v_add_f32_e32 v34, v34, v155
	v_add_f32_e32 v35, v35, v156
	v_cvt_pk_bf16_f32 v155, v155, v156
	v_add_f32_e32 v32, v32, v157
	v_add_f32_e32 v33, v33, v178
	v_cvt_pk_bf16_f32 v156, v157, v178
	v_add_f32_e32 v34, v34, v175
	v_add_f32_e32 v35, v35, v176
	v_cvt_pk_bf16_f32 v157, v175, v176
	v_mfma_f32_32x32x16_bf16 v[80:95], v[228:231], v[116:119], v[80:95]
	s_and_b64 vcc, exec, s[6:7]
	s_waitcnt lgkmcnt(0)
	v_mfma_f32_32x32x16_bf16 v[16:31], v[52:55], v[154:157], v[16:31]
	v_mfma_f32_32x32x16_bf16 v[0:15], v[48:51], v[154:157], v[0:15]
	v_add_f32_e32 v32, v32, v181
	v_add_f32_e32 v33, v33, v186
	v_cvt_pk_bf16_f32 v48, v181, v186
	v_add_f32_e32 v34, v34, v184
	v_add_f32_e32 v35, v35, v185
	v_cvt_pk_bf16_f32 v49, v184, v185
	v_add_f32_e32 v32, v32, v189
	v_add_f32_e32 v33, v33, v190
	v_cvt_pk_bf16_f32 v50, v189, v190
	v_cvt_pk_bf16_f32 v51, v202, v203
	v_add_f32_e32 v34, v34, v202
	v_add_f32_e32 v35, v35, v203
	v_mfma_f32_32x32x16_bf16 v[16:31], v[60:63], v[48:51], v[16:31]
	v_mfma_f32_32x32x16_bf16 v[0:15], v[56:59], v[48:51], v[0:15]
	v_add_f32_e32 v32, v32, v152
	v_add_f32_e32 v33, v33, v153
	v_cvt_pk_bf16_f32 v52, v152, v153
	v_add_f32_e32 v34, v34, v167
	v_add_f32_e32 v35, v35, v169
	v_cvt_pk_bf16_f32 v53, v167, v169
	v_add_f32_e32 v32, v32, v179
	v_add_f32_e32 v33, v33, v174
	v_cvt_pk_bf16_f32 v54, v179, v174
	v_cvt_pk_bf16_f32 v55, v177, v180
	v_add_f32_e32 v34, v34, v177
	v_add_f32_e32 v35, v35, v180
	v_mfma_f32_32x32x16_bf16 v[16:31], v[68:71], v[52:55], v[16:31]
	v_mfma_f32_32x32x16_bf16 v[0:15], v[64:67], v[52:55], v[0:15]
	v_add_f32_e32 v32, v32, v182
	v_add_f32_e32 v33, v33, v183
	v_cvt_pk_bf16_f32 v48, v182, v183
	v_add_f32_e32 v34, v34, v187
	v_add_f32_e32 v35, v35, v188
	v_cvt_pk_bf16_f32 v49, v187, v188
	v_add_f32_e32 v32, v32, v191
	v_add_f32_e32 v33, v33, v201
	v_cvt_pk_bf16_f32 v50, v191, v201
	v_cvt_pk_bf16_f32 v51, v204, v205
	v_add_f32_e32 v34, v34, v204
	v_add_f32_e32 v35, v35, v205
	v_mfma_f32_32x32x16_bf16 v[16:31], v[76:79], v[48:51], v[16:31]
	v_mfma_f32_32x32x16_bf16 v[0:15], v[72:75], v[48:51], v[0:15]
	s_cbranch_vccnz .LBB0_1222
	v_pk_add_f32 v[102:103], v[102:103], v[172:173] op_sel_hi:[1,0] neg_lo:[0,1] neg_hi:[0,1]
	v_pk_add_f32 v[110:111], v[110:111], v[172:173] op_sel_hi:[1,0] neg_lo:[0,1] neg_hi:[0,1]
	v_pk_add_f32 v[96:97], v[96:97], v[172:173] op_sel_hi:[1,0] neg_lo:[0,1] neg_hi:[0,1]
	v_pk_add_f32 v[98:99], v[98:99], v[172:173] op_sel_hi:[1,0] neg_lo:[0,1] neg_hi:[0,1]
	v_pk_add_f32 v[100:101], v[100:101], v[172:173] op_sel_hi:[1,0] neg_lo:[0,1] neg_hi:[0,1]
	v_pk_add_f32 v[104:105], v[104:105], v[172:173] op_sel_hi:[1,0] neg_lo:[0,1] neg_hi:[0,1]
	v_pk_add_f32 v[106:107], v[106:107], v[172:173] op_sel_hi:[1,0] neg_lo:[0,1] neg_hi:[0,1]
	v_pk_add_f32 v[108:109], v[108:109], v[172:173] op_sel_hi:[1,0] neg_lo:[0,1] neg_hi:[0,1]
	v_pk_add_f32 v[94:95], v[94:95], v[172:173] op_sel_hi:[1,0] neg_lo:[0,1] neg_hi:[0,1]
	v_max_f32_e32 v50, v102, v103
	v_max_f32_e32 v53, v110, v111
	v_pk_add_f32 v[82:83], v[82:83], v[172:173] op_sel_hi:[1,0] neg_lo:[0,1] neg_hi:[0,1]
	v_pk_add_f32 v[86:87], v[86:87], v[172:173] op_sel_hi:[1,0] neg_lo:[0,1] neg_hi:[0,1]
	v_pk_add_f32 v[88:89], v[88:89], v[172:173] op_sel_hi:[1,0] neg_lo:[0,1] neg_hi:[0,1]
	v_pk_add_f32 v[90:91], v[90:91], v[172:173] op_sel_hi:[1,0] neg_lo:[0,1] neg_hi:[0,1]
	v_pk_add_f32 v[92:93], v[92:93], v[172:173] op_sel_hi:[1,0] neg_lo:[0,1] neg_hi:[0,1]
	v_max_f32_e32 v48, v96, v97
	v_max_f32_e32 v49, v98, v99
	v_max3_f32 v50, v100, v101, v50
	v_max_f32_e32 v51, v104, v105
	v_max_f32_e32 v52, v106, v107
	v_max3_f32 v53, v108, v109, v53
	v_max_f32_e32 v54, v94, v95
	v_pk_add_f32 v[80:81], v[80:81], v[172:173] op_sel_hi:[1,0] neg_lo:[0,1] neg_hi:[0,1]
	v_pk_add_f32 v[84:85], v[84:85], v[172:173] op_sel_hi:[1,0] neg_lo:[0,1] neg_hi:[0,1]
	v_max3_f32 v48, v48, v49, v50
	v_max3_f32 v49, v51, v52, v53
	v_max_f32_e32 v50, v82, v83
	v_max_f32_e32 v51, v86, v87
	v_max_f32_e32 v52, v88, v89
	v_max_f32_e32 v53, v90, v91
	v_max3_f32 v54, v92, v93, v54
	v_max3_f32 v50, v80, v81, v50
	v_max3_f32 v51, v84, v85, v51
	v_max3_f32 v52, v52, v53, v54
	v_max3_f32 v50, v50, v51, v52
	v_max3_f32 v48, v48, v49, v50
	ds_bpermute_b32 v49, v218, v48
	s_mov_b32 s8, 0x41000000
	s_waitcnt lgkmcnt(0)
	v_max_f32_e32 v49, v49, v49
	v_max_f32_e32 v48, v48, v49
	v_cmp_lt_f32_e32 vcc, s8, v48
	s_cbranch_vccz .LBB0_1222
	v_max_f32_e32 v48, v48, v48
	v_max_f32_e32 v49, 0, v48
	v_exp_f32_e64 v48, -v49
	v_sub_f32_e32 v96, v96, v49
	v_sub_f32_e32 v97, v97, v49
	v_sub_f32_e32 v98, v98, v49
	v_sub_f32_e32 v99, v99, v49
	v_sub_f32_e32 v100, v100, v49
	v_sub_f32_e32 v101, v101, v49
	v_sub_f32_e32 v102, v102, v49
	v_sub_f32_e32 v103, v103, v49
	v_sub_f32_e32 v104, v104, v49
	v_sub_f32_e32 v105, v105, v49
	v_sub_f32_e32 v106, v106, v49
	v_sub_f32_e32 v107, v107, v49
	v_sub_f32_e32 v108, v108, v49
	v_sub_f32_e32 v109, v109, v49
	v_sub_f32_e32 v110, v110, v49
	v_sub_f32_e32 v111, v111, v49
	v_sub_f32_e32 v80, v80, v49
	v_sub_f32_e32 v81, v81, v49
	v_sub_f32_e32 v82, v82, v49
	v_sub_f32_e32 v83, v83, v49
	v_sub_f32_e32 v84, v84, v49
	v_sub_f32_e32 v85, v85, v49
	v_sub_f32_e32 v86, v86, v49
	v_sub_f32_e32 v87, v87, v49
	v_sub_f32_e32 v88, v88, v49
	v_sub_f32_e32 v89, v89, v49
	v_sub_f32_e32 v90, v90, v49
	v_sub_f32_e32 v91, v91, v49
	v_sub_f32_e32 v92, v92, v49
	v_sub_f32_e32 v93, v93, v49
	v_sub_f32_e32 v94, v94, v49
	v_sub_f32_e32 v95, v95, v49
	v_pk_mul_f32 v[14:15], v[14:15], v[48:49] op_sel_hi:[1,0]
	v_pk_mul_f32 v[12:13], v[12:13], v[48:49] op_sel_hi:[1,0]
	v_pk_mul_f32 v[10:11], v[10:11], v[48:49] op_sel_hi:[1,0]
	v_pk_mul_f32 v[8:9], v[8:9], v[48:49] op_sel_hi:[1,0]
	v_pk_mul_f32 v[6:7], v[6:7], v[48:49] op_sel_hi:[1,0]
	v_pk_mul_f32 v[4:5], v[4:5], v[48:49] op_sel_hi:[1,0]
	v_pk_mul_f32 v[2:3], v[2:3], v[48:49] op_sel_hi:[1,0]
	v_pk_mul_f32 v[0:1], v[0:1], v[48:49] op_sel_hi:[1,0]
	v_pk_mul_f32 v[30:31], v[30:31], v[48:49] op_sel_hi:[1,0]
	v_pk_mul_f32 v[28:29], v[28:29], v[48:49] op_sel_hi:[1,0]
	v_pk_mul_f32 v[26:27], v[26:27], v[48:49] op_sel_hi:[1,0]
	v_pk_mul_f32 v[24:25], v[24:25], v[48:49] op_sel_hi:[1,0]
	v_pk_mul_f32 v[22:23], v[22:23], v[48:49] op_sel_hi:[1,0]
	v_pk_mul_f32 v[20:21], v[20:21], v[48:49] op_sel_hi:[1,0]
	v_pk_mul_f32 v[18:19], v[18:19], v[48:49] op_sel_hi:[1,0]
	v_pk_mul_f32 v[16:17], v[16:17], v[48:49] op_sel_hi:[1,0]
	v_pk_mul_f32 v[46:47], v[46:47], v[48:49] op_sel_hi:[1,0]
	v_pk_mul_f32 v[44:45], v[44:45], v[48:49] op_sel_hi:[1,0]
	v_pk_mul_f32 v[42:43], v[42:43], v[48:49] op_sel_hi:[1,0]
	v_pk_mul_f32 v[40:41], v[40:41], v[48:49] op_sel_hi:[1,0]
	v_pk_mul_f32 v[38:39], v[38:39], v[48:49] op_sel_hi:[1,0]
	v_pk_mul_f32 v[36:37], v[36:37], v[48:49] op_sel_hi:[1,0]
	v_pk_mul_f32 v[34:35], v[34:35], v[48:49] op_sel_hi:[1,0]
	v_pk_mul_f32 v[32:33], v[32:33], v[48:49] op_sel_hi:[1,0]
	v_add_f32_e32 v172, v172, v49
.LBB0_1222:
	ds_read_b128 v[48:51], v199
	ds_read_b128 v[64:67], v200
	ds_read_b128 v[68:71], v199 offset:64
	ds_read_b128 v[72:75], v200 offset:64
	ds_read_b128 v[76:79], v199 offset:128
	ds_read_b128 v[154:157], v200 offset:128
	v_exp_f32_e32 v96, v96
	v_exp_f32_e32 v97, v97
	v_exp_f32_e32 v98, v98
	s_waitcnt lgkmcnt(0)
	v_mfma_f32_32x32x16_bf16 v[48:63], v[48:51], v[136:139], 0
	v_exp_f32_e32 v136, v80
	v_exp_f32_e32 v137, v81
	v_exp_f32_e32 v99, v99
	v_exp_f32_e32 v100, v100
	v_exp_f32_e32 v101, v101
	v_exp_f32_e32 v102, v102
	v_exp_f32_e32 v103, v103
	v_mfma_f32_32x32x16_bf16 v[48:63], v[64:67], v[132:135], v[48:63]
	v_exp_f32_e32 v132, v82
	v_exp_f32_e32 v133, v83
	v_exp_f32_e32 v134, v84
	v_exp_f32_e32 v104, v104
	v_exp_f32_e32 v105, v105
	v_exp_f32_e32 v106, v106
	v_exp_f32_e32 v107, v107
	v_mfma_f32_32x32x16_bf16 v[48:63], v[68:71], v[128:131], v[48:63]
	v_exp_f32_e32 v128, v85
	v_exp_f32_e32 v129, v86
	v_exp_f32_e32 v130, v87
	v_exp_f32_e32 v108, v108
	v_exp_f32_e32 v109, v109
	v_exp_f32_e32 v92, v92
	v_exp_f32_e32 v93, v93
	v_mfma_f32_32x32x16_bf16 v[48:63], v[72:75], v[124:127], v[48:63]
	v_exp_f32_e32 v124, v88
	v_exp_f32_e32 v125, v89
	v_exp_f32_e32 v126, v90
	v_exp_f32_e32 v127, v91
	v_exp_f32_e32 v110, v110
	v_exp_f32_e32 v111, v111
	v_exp_f32_e32 v94, v94
	v_mfma_f32_32x32x16_bf16 v[48:63], v[76:79], v[120:123], v[48:63]
	v_exp_f32_e32 v95, v95
	v_mfma_f32_32x32x16_bf16 v[48:63], v[154:157], v[116:119], v[48:63]
	s_nop 11
	ds_read_b128 v[56:59], v192 offset:24576
	ds_read_b128 v[60:63], v192 offset:28672
	ds_read_b128 v[64:67], v198 offset:24576
	ds_read_b128 v[68:71], v198 offset:28672
	ds_read_b128 v[72:75], v194 offset:24576
	ds_read_b128 v[76:79], v194 offset:28672
	ds_read_b128 v[80:83], v196 offset:24576
	ds_read_b128 v[84:87], v196 offset:28672
	v_add_f32_e32 v32, v32, v96
	v_add_f32_e32 v33, v33, v97
	v_cvt_pk_bf16_f32 v88, v96, v97
	v_add_f32_e32 v34, v34, v98
	v_add_f32_e32 v35, v35, v99
	v_cvt_pk_bf16_f32 v89, v98, v99
	v_add_f32_e32 v32, v32, v100
	v_add_f32_e32 v33, v33, v101
	v_cvt_pk_bf16_f32 v90, v100, v101
	v_add_f32_e32 v34, v34, v102
	v_add_f32_e32 v35, v35, v103
	v_cvt_pk_bf16_f32 v91, v102, v103
	s_cmp_eq_u32 s64, 0
	s_cbranch_scc1 .Lmla_late_skip3
	s_waitcnt vmcnt(0)
	s_barrier
.Lmla_late_skip3:
	s_and_b64 vcc, exec, s[6:7]
	s_waitcnt lgkmcnt(0)
	v_mfma_f32_32x32x16_bf16 v[16:31], v[60:63], v[88:91], v[16:31]
	v_mfma_f32_32x32x16_bf16 v[0:15], v[56:59], v[88:91], v[0:15]
	v_add_f32_e32 v32, v32, v104
	v_add_f32_e32 v33, v33, v105
	v_cvt_pk_bf16_f32 v56, v104, v105
	v_add_f32_e32 v34, v34, v106
	v_add_f32_e32 v35, v35, v107
	v_cvt_pk_bf16_f32 v57, v106, v107
	v_add_f32_e32 v32, v32, v108
	v_add_f32_e32 v33, v33, v109
	v_cvt_pk_bf16_f32 v58, v108, v109
	v_add_f32_e32 v34, v34, v110
	v_add_f32_e32 v35, v35, v111
	v_cvt_pk_bf16_f32 v59, v110, v111
	s_nop 1
	v_mfma_f32_32x32x16_bf16 v[16:31], v[68:71], v[56:59], v[16:31]
	v_mfma_f32_32x32x16_bf16 v[0:15], v[64:67], v[56:59], v[0:15]
	v_add_f32_e32 v32, v32, v136
	v_add_f32_e32 v33, v33, v137
	v_cvt_pk_bf16_f32 v56, v136, v137
	v_add_f32_e32 v34, v34, v132
	v_add_f32_e32 v35, v35, v133
	v_cvt_pk_bf16_f32 v57, v132, v133
	v_add_f32_e32 v32, v32, v134
	v_add_f32_e32 v33, v33, v128
	v_cvt_pk_bf16_f32 v58, v134, v128
	v_add_f32_e32 v34, v34, v129
	v_add_f32_e32 v35, v35, v130
	v_cvt_pk_bf16_f32 v59, v129, v130
	s_nop 1
	v_mfma_f32_32x32x16_bf16 v[16:31], v[76:79], v[56:59], v[16:31]
	v_mfma_f32_32x32x16_bf16 v[0:15], v[72:75], v[56:59], v[0:15]
	v_add_f32_e32 v32, v32, v124
	v_add_f32_e32 v33, v33, v125
	v_cvt_pk_bf16_f32 v56, v124, v125
	v_add_f32_e32 v34, v34, v126
	v_add_f32_e32 v35, v35, v127
	v_cvt_pk_bf16_f32 v57, v126, v127
	v_add_f32_e32 v32, v32, v92
	v_add_f32_e32 v33, v33, v93
	v_cvt_pk_bf16_f32 v58, v92, v93
	v_add_f32_e32 v34, v34, v94
	v_add_f32_e32 v35, v35, v95
	v_cvt_pk_bf16_f32 v59, v94, v95
	s_nop 1
	v_mfma_f32_32x32x16_bf16 v[16:31], v[84:87], v[56:59], v[16:31]
	v_mfma_f32_32x32x16_bf16 v[0:15], v[80:83], v[56:59], v[0:15]
	s_cbranch_vccnz .LBB0_1176
	v_pk_add_f32 v[50:51], v[50:51], v[172:173] op_sel_hi:[1,0] neg_lo:[0,1] neg_hi:[0,1]
	v_pk_add_f32 v[54:55], v[54:55], v[172:173] op_sel_hi:[1,0] neg_lo:[0,1] neg_hi:[0,1]
	v_pk_add_f32 v[48:49], v[48:49], v[172:173] op_sel_hi:[1,0] neg_lo:[0,1] neg_hi:[0,1]
	v_pk_add_f32 v[52:53], v[52:53], v[172:173] op_sel_hi:[1,0] neg_lo:[0,1] neg_hi:[0,1]
	v_max_f32_e32 v57, v50, v51
	v_max_f32_e32 v58, v54, v55
	v_sub_f32_e32 v56, 0xff800000, v172
	v_max3_f32 v57, v48, v49, v57
	v_max3_f32 v58, v52, v53, v58
	v_max3_f32 v57, v57, v58, v56
	ds_bpermute_b32 v58, v218, v57
	s_mov_b32 s6, 0x41000000
	s_waitcnt lgkmcnt(0)
	v_max_f32_e32 v58, v58, v58
	v_max_f32_e32 v57, v57, v58
	v_cmp_lt_f32_e32 vcc, s6, v57
	s_cbranch_vccz .LBB0_1177
	v_max_f32_e32 v57, v57, v57
	v_max_f32_e32 v58, 0, v57
	v_exp_f32_e64 v60, -v58
	v_sub_f32_e32 v56, v56, v58
	v_pk_add_f32 v[48:49], v[48:49], v[58:59] op_sel_hi:[1,0] neg_lo:[0,1] neg_hi:[0,1]
	v_pk_add_f32 v[50:51], v[50:51], v[58:59] op_sel_hi:[1,0] neg_lo:[0,1] neg_hi:[0,1]
	v_pk_add_f32 v[52:53], v[52:53], v[58:59] op_sel_hi:[1,0] neg_lo:[0,1] neg_hi:[0,1]
	v_pk_add_f32 v[54:55], v[54:55], v[58:59] op_sel_hi:[1,0] neg_lo:[0,1] neg_hi:[0,1]
	v_pk_mul_f32 v[14:15], v[14:15], v[60:61] op_sel_hi:[1,0]
	v_pk_mul_f32 v[12:13], v[12:13], v[60:61] op_sel_hi:[1,0]
	v_pk_mul_f32 v[10:11], v[10:11], v[60:61] op_sel_hi:[1,0]
	v_pk_mul_f32 v[8:9], v[8:9], v[60:61] op_sel_hi:[1,0]
	v_pk_mul_f32 v[6:7], v[6:7], v[60:61] op_sel_hi:[1,0]
	v_pk_mul_f32 v[4:5], v[4:5], v[60:61] op_sel_hi:[1,0]
	v_pk_mul_f32 v[2:3], v[2:3], v[60:61] op_sel_hi:[1,0]
	v_pk_mul_f32 v[0:1], v[0:1], v[60:61] op_sel_hi:[1,0]
	v_pk_mul_f32 v[30:31], v[30:31], v[60:61] op_sel_hi:[1,0]
	v_pk_mul_f32 v[28:29], v[28:29], v[60:61] op_sel_hi:[1,0]
	v_pk_mul_f32 v[26:27], v[26:27], v[60:61] op_sel_hi:[1,0]
	v_pk_mul_f32 v[24:25], v[24:25], v[60:61] op_sel_hi:[1,0]
	v_pk_mul_f32 v[22:23], v[22:23], v[60:61] op_sel_hi:[1,0]
	v_pk_mul_f32 v[20:21], v[20:21], v[60:61] op_sel_hi:[1,0]
	v_pk_mul_f32 v[18:19], v[18:19], v[60:61] op_sel_hi:[1,0]
	v_pk_mul_f32 v[16:17], v[16:17], v[60:61] op_sel_hi:[1,0]
	v_pk_mul_f32 v[46:47], v[46:47], v[60:61] op_sel_hi:[1,0]
	v_pk_mul_f32 v[44:45], v[44:45], v[60:61] op_sel_hi:[1,0]
	v_pk_mul_f32 v[42:43], v[42:43], v[60:61] op_sel_hi:[1,0]
	v_pk_mul_f32 v[40:41], v[40:41], v[60:61] op_sel_hi:[1,0]
	v_pk_mul_f32 v[38:39], v[38:39], v[60:61] op_sel_hi:[1,0]
	v_pk_mul_f32 v[36:37], v[36:37], v[60:61] op_sel_hi:[1,0]
	v_pk_mul_f32 v[34:35], v[34:35], v[60:61] op_sel_hi:[1,0]
	v_pk_mul_f32 v[32:33], v[32:33], v[60:61] op_sel_hi:[1,0]
	s_branch .LBB0_1177
